# row-norm phases 1 and 15: software-pipelined loops (next iteration's 8 row loads issued right after this iteration's modulation loads, two register sets, unrolled by two); three phase-0 transposer cop
# speedup vs baseline: 1.0068x; 1.0068x over previous
.LBB0_19:
	s_mov_b64 s[8:9], 0
	s_movk_i32 s15, 0x80
	s_andn2_b64 vcc, exec, s[28:29]
	s_mov_b64 s[28:29], 0
	s_cbranch_vccnz .LBB0_24
	s_cmpk_gt_i32 s6, 0x7fff
	s_cbranch_scc1 .LBB0_23
	s_load_dwordx2 s[42:43], s[0:1], 0xa0
	s_load_dwordx2 s[40:41], s[0:1], 0xb8
	v_lshlrev_b32_e32 v18, 4, v227
	s_add_u32 s22, s36, 0x3600000
	s_addc_u32 s23, s37, 0
	s_waitcnt lgkmcnt(0)
	v_mov_b32_e32 v200, v18
	v_mov_b32_e32 v201, v0
	v_lshl_add_u64 v[200:201], s[42:43], 0, v[200:201]
	s_ashr_i32 s7, s6, 31
	s_lshl_b32 s42, s30, 4
	v_lshlrev_b32_e32 v28, 3, v227
	v_mov_b32_e32 v29, v0
	s_lshl_b64 s[26:27], s[6:7], 11
	v_lshl_add_u64 v[36:37], s[22:23], 0, v[28:29]
	s_add_u32 s22, s22, s26
	s_addc_u32 s23, s23, s27
	s_ashr_i32 s43, s42, 31
	v_mov_b32_e32 v19, v0
	v_lshl_add_u64 v[38:39], s[22:23], 0, v[28:29]
	s_lshl_b64 s[22:23], s[42:43], 11
	s_lshl_b64 s[26:27], s[6:7], 12
	v_lshl_add_u64 v[34:35], s[40:41], 0, v[18:19]
	v_lshlrev_b32_e32 v20, 2, v227
	s_add_u32 s40, s40, s26
	v_or_b32_e32 v22, 0x100, v20
	v_or_b32_e32 v24, 0x200, v20
	v_or_b32_e32 v26, 0x300, v20
	s_addc_u32 s41, s41, s27
	v_lshl_add_u64 v[40:41], s[40:41], 0, v[18:19]
	s_lshl_b64 s[28:29], s[42:43], 12
	v_lshlrev_b32_e32 v1, 2, v20
	v_lshlrev_b32_e32 v42, 2, v22
	v_lshlrev_b32_e32 v43, 2, v24
	v_lshlrev_b32_e32 v44, 2, v26
	s_mov_b32 s7, s6
	global_load_dwordx4 v[30:33], v[40:41], off nt
	global_load_dwordx4 v[26:29], v[40:41], off offset:1024 nt
	global_load_dwordx4 v[22:25], v[40:41], off offset:2048 nt
	global_load_dwordx4 v[18:21], v[40:41], off offset:3072 nt
	s_add_i32 s43, s21, s7
	s_cmp_lt_i32 s43, 0x8000
	s_cselect_b32 s40, s43, s7
	s_ashr_i32 s41, s40, 31
	s_lshl_b64 s[38:39], s[40:41], 12
	v_lshl_add_u64 v[58:59], v[34:35], 0, s[38:39]
	global_load_dwordx4 v[46:49], v[58:59], off nt
	global_load_dwordx4 v[50:53], v[58:59], off offset:1024 nt
	global_load_dwordx4 v[54:57], v[58:59], off offset:2048 nt
	s_nop 0
	global_load_dwordx4 v[58:61], v[58:59], off offset:3072 nt
	global_load_dwordx4 v[2:5], v[200:201], off
	global_load_dwordx4 v[6:9], v[200:201], off offset:1024
	global_load_dwordx4 v[10:13], v[200:201], off offset:2048
	global_load_dwordx4 v[14:17], v[200:201], off offset:3072
	global_load_dwordx4 v[2:5], v[200:201], off
	global_load_dwordx4 v[6:9], v[200:201], off offset:1024
	global_load_dwordx4 v[10:13], v[200:201], off offset:2048
	global_load_dwordx4 v[14:17], v[200:201], off offset:3072
.Lnpf2_a:
	s_lshr_b32 s43, s7, 11
	s_mul_i32 s26, s43, 0x1800
	s_ashr_i32 s27, s26, 31
	s_lshl_b64 s[26:27], s[26:27], 2
	s_add_u32 s26, s36, s26
	s_addc_u32 s27, s37, s27
	s_add_u32 s26, s26, 0x3000
	s_addc_u32 s27, s27, 0
	s_add_u32 s38, s26, 0x1000
	s_addc_u32 s39, s27, 0
	s_lshr_b32 s43, s40, 11
	global_load_dwordx4 v[62:65], v1, s[26:27]
	global_load_dwordx4 v[66:69], v1, s[26:27] offset:1024
	global_load_dwordx4 v[70:73], v1, s[26:27] offset:2048
	global_load_dwordx4 v[74:77], v1, s[26:27] offset:3072
	s_mul_i32 s26, s43, 0x1800
	s_ashr_i32 s27, s26, 31
	s_lshl_b64 s[26:27], s[26:27], 2
	global_load_dwordx4 v[78:81], v1, s[38:39]
	global_load_dwordx4 v[82:85], v42, s[38:39]
	global_load_dwordx4 v[86:89], v43, s[38:39]
	global_load_dwordx4 v[90:93], v44, s[38:39]
	s_add_u32 s26, s36, s26
	s_addc_u32 s27, s37, s27
	s_add_u32 s26, s26, 0x3000
	s_addc_u32 s27, s27, 0
	s_add_u32 s38, s26, 0x1000
	s_addc_u32 s39, s27, 0
	global_load_dwordx4 v[94:97], v1, s[26:27]
	global_load_dwordx4 v[98:101], v1, s[26:27] offset:1024
	global_load_dwordx4 v[102:105], v1, s[26:27] offset:2048
	global_load_dwordx4 v[106:109], v1, s[26:27] offset:3072
	global_load_dwordx4 v[110:113], v1, s[38:39]
	global_load_dwordx4 v[114:117], v42, s[38:39]
	global_load_dwordx4 v[118:121], v43, s[38:39]
	global_load_dwordx4 v[122:125], v44, s[38:39]
	s_lshl_b64 s[40:41], s[40:41], 11
	v_lshl_add_u64 v[126:127], v[36:37], 0, s[40:41]
	s_add_i32 s7, s7, s42
	v_lshl_add_u64 v[40:41], v[40:41], 0, s[28:29]
	s_cmpk_gt_i32 s7, 0x7fff
	s_cselect_b64 vcc, -1, 0
	s_add_i32 s43, s21, s7
	s_cmp_lt_i32 s43, 0x8000
	s_cselect_b32 s40, s43, s7
	s_ashr_i32 s41, s40, 31
	s_lshl_b64 s[38:39], s[40:41], 12
	v_lshl_add_u64 v[196:197], v[34:35], 0, s[38:39]
	v_cndmask_b32_e32 v202, v40, v200, vcc
	v_cndmask_b32_e32 v203, v41, v201, vcc
	v_cndmask_b32_e32 v196, v196, v200, vcc
	v_cndmask_b32_e32 v197, v197, v201, vcc
	global_load_dwordx4 v[180:183], v[202:203], off nt
	global_load_dwordx4 v[176:179], v[202:203], off offset:1024 nt
	global_load_dwordx4 v[172:175], v[202:203], off offset:2048 nt
	global_load_dwordx4 v[168:171], v[202:203], off offset:3072 nt
	global_load_dwordx4 v[184:187], v[196:197], off nt
	global_load_dwordx4 v[188:191], v[196:197], off offset:1024 nt
	global_load_dwordx4 v[192:195], v[196:197], off offset:2048 nt
	s_nop 0
	global_load_dwordx4 v[196:199], v[196:197], off offset:3072 nt
	s_cmpk_gt_i32 s7, 0x7fff
	s_waitcnt vmcnt(39)
	v_mul_f32_e32 v45, v31, v31
	v_mul_f32_e32 v128, v33, v33
	s_waitcnt vmcnt(38)
	v_mul_f32_e32 v129, v27, v27
	v_mul_f32_e32 v130, v29, v29
	s_waitcnt vmcnt(37)
	v_mul_f32_e32 v131, v23, v23
	v_mul_f32_e32 v132, v25, v25
	v_fmac_f32_e32 v45, v30, v30
	v_fmac_f32_e32 v128, v32, v32
	v_fmac_f32_e32 v129, v26, v26
	v_fmac_f32_e32 v130, v28, v28
	s_waitcnt vmcnt(36)
	v_mul_f32_e32 v133, v19, v19
	v_mul_f32_e32 v134, v21, v21
	v_fmac_f32_e32 v131, v22, v22
	v_fmac_f32_e32 v132, v24, v24
	v_add_f32_e32 v45, v45, v128
	v_add_f32_e32 v128, v129, v130
	v_fmac_f32_e32 v133, v18, v18
	v_fmac_f32_e32 v134, v20, v20
	v_add_f32_e32 v129, v131, v132
	v_add_f32_e32 v45, v45, v128
	v_add_f32_e32 v130, v133, v134
	v_add_f32_e32 v45, v45, v129
	v_add_f32_e32 v45, v45, v130
	s_waitcnt vmcnt(35)
	v_mul_f32_e32 v128, v47, v47
	v_mul_f32_e32 v129, v49, v49
	s_waitcnt vmcnt(34)
	v_mul_f32_e32 v130, v51, v51
	v_mul_f32_e32 v131, v53, v53
	v_add_f32_dpp v45, v45, v45 quad_perm:[1,0,3,2] row_mask:0xf bank_mask:0xf bound_ctrl:1
	s_waitcnt vmcnt(33)
	v_mul_f32_e32 v132, v55, v55
	v_mul_f32_e32 v133, v57, v57
	v_fmac_f32_e32 v128, v46, v46
	v_fmac_f32_e32 v129, v48, v48
	v_fmac_f32_e32 v130, v50, v50
	v_fmac_f32_e32 v131, v52, v52
	v_add_f32_dpp v45, v45, v45 quad_perm:[2,3,0,1] row_mask:0xf bank_mask:0xf bound_ctrl:1
	s_waitcnt vmcnt(32)
	v_mul_f32_e32 v134, v59, v59
	v_mul_f32_e32 v135, v61, v61
	v_fmac_f32_e32 v132, v54, v54
	v_fmac_f32_e32 v133, v56, v56
	v_add_f32_e32 v128, v128, v129
	v_add_f32_e32 v129, v130, v131
	v_add_f32_dpp v45, v45, v45 row_half_mirror row_mask:0xf bank_mask:0xf bound_ctrl:1
	v_fmac_f32_e32 v134, v58, v58
	v_fmac_f32_e32 v135, v60, v60
	v_add_f32_e32 v130, v132, v133
	v_add_f32_e32 v128, v128, v129
	v_add_f32_dpp v45, v45, v45 row_mirror row_mask:0xf bank_mask:0xf bound_ctrl:1
	v_add_f32_e32 v131, v134, v135
	v_add_f32_e32 v128, v128, v130
	v_mov_b32_e32 v129, v45
	v_add_f32_e32 v128, v128, v131
	s_nop 0
	v_permlane16_swap_b32_e32 v45, v129
	v_add_f32_e32 v45, v45, v129
	v_add_f32_dpp v128, v128, v128 quad_perm:[1,0,3,2] row_mask:0xf bank_mask:0xf bound_ctrl:1
	v_mov_b32_e32 v129, v45
	s_nop 1
	v_permlane32_swap_b32_e32 v45, v129
	v_add_f32_dpp v128, v128, v128 quad_perm:[2,3,0,1] row_mask:0xf bank_mask:0xf bound_ctrl:1
	v_add_f32_e32 v45, v45, v129
	v_fmamk_f32 v45, v45, 0x3a800000, v207
	v_add_f32_dpp v128, v128, v128 row_half_mirror row_mask:0xf bank_mask:0xf bound_ctrl:1
	s_waitcnt vmcnt(19)
	v_pk_add_f32 v[78:79], v[78:79], 1.0 op_sel_hi:[1,0]
	v_pk_add_f32 v[80:81], v[80:81], 1.0 op_sel_hi:[1,0]
	v_add_f32_dpp v129, v128, v128 row_mirror row_mask:0xf bank_mask:0xf bound_ctrl:1
	v_mov_b32_e32 v130, v129
	s_nop 1
	v_permlane16_swap_b32_e32 v129, v130
	v_rsq_f32_e32 v128, v45
	v_add_f32_e32 v45, v129, v130
	v_mov_b32_e32 v129, v45
	s_nop 1
	v_permlane32_swap_b32_e32 v45, v129
	v_add_f32_e32 v45, v45, v129
	v_pk_mul_f32 v[30:31], v[30:31], v[128:129] op_sel_hi:[1,0]
	v_fmamk_f32 v45, v45, 0x3a800000, v207
	v_pk_mul_f32 v[30:31], v[2:3], v[30:31]
	v_pk_mul_f32 v[32:33], v[32:33], v[128:129] op_sel_hi:[1,0]
	v_pk_mul_f32 v[20:21], v[20:21], v[128:129] op_sel_hi:[1,0]
	v_pk_mul_f32 v[18:19], v[18:19], v[128:129] op_sel_hi:[1,0]
	v_pk_fma_f32 v[30:31], v[78:79], v[30:31], v[62:63]
	v_rsq_f32_e32 v62, v45
	s_waitcnt vmcnt(16)
	v_pk_add_f32 v[92:93], v[92:93], 1.0 op_sel_hi:[1,0]
	v_pk_add_f32 v[90:91], v[90:91], 1.0 op_sel_hi:[1,0]
	v_pk_mul_f32 v[28:29], v[28:29], v[128:129] op_sel_hi:[1,0]
	v_pk_mul_f32 v[26:27], v[26:27], v[128:129] op_sel_hi:[1,0]
	v_pk_mul_f32 v[24:25], v[24:25], v[128:129] op_sel_hi:[1,0]
	v_pk_mul_f32 v[22:23], v[22:23], v[128:129] op_sel_hi:[1,0]
	v_pk_mul_f32 v[32:33], v[4:5], v[32:33]
	v_pk_mul_f32 v[18:19], v[14:15], v[18:19]
	v_pk_mul_f32 v[20:21], v[16:17], v[20:21]
	v_pk_add_f32 v[84:85], v[84:85], 1.0 op_sel_hi:[1,0]
	v_pk_add_f32 v[82:83], v[82:83], 1.0 op_sel_hi:[1,0]
	v_pk_add_f32 v[88:89], v[88:89], 1.0 op_sel_hi:[1,0]
	v_pk_add_f32 v[86:87], v[86:87], 1.0 op_sel_hi:[1,0]
	v_pk_mul_f32 v[26:27], v[6:7], v[26:27]
	v_pk_mul_f32 v[28:29], v[8:9], v[28:29]
	v_pk_mul_f32 v[22:23], v[10:11], v[22:23]
	v_pk_mul_f32 v[24:25], v[12:13], v[24:25]
	v_pk_fma_f32 v[32:33], v[80:81], v[32:33], v[64:65]
	v_pk_fma_f32 v[20:21], v[20:21], v[92:93], v[76:77]
	v_pk_fma_f32 v[18:19], v[18:19], v[90:91], v[74:75]
	v_pk_fma_f32 v[28:29], v[28:29], v[84:85], v[68:69]
	v_pk_fma_f32 v[26:27], v[26:27], v[82:83], v[66:67]
	v_pk_fma_f32 v[24:25], v[24:25], v[88:89], v[72:73]
	v_pk_fma_f32 v[22:23], v[22:23], v[86:87], v[70:71]
	v_cvt_pk_bf16_f32 v30, v30, v31
	v_cvt_pk_bf16_f32 v31, v32, v33
	v_cvt_pk_bf16_f32 v18, v18, v19
	v_cvt_pk_bf16_f32 v19, v20, v21
	v_cvt_pk_bf16_f32 v26, v26, v27
	v_cvt_pk_bf16_f32 v27, v28, v29
	v_cvt_pk_bf16_f32 v22, v22, v23
	v_cvt_pk_bf16_f32 v23, v24, v25
	global_store_dwordx2 v[38:39], v[30:31], off sc1
	global_store_dwordx2 v[38:39], v[26:27], off offset:512 sc1
	global_store_dwordx2 v[38:39], v[22:23], off offset:1024 sc1
	global_store_dwordx2 v[38:39], v[18:19], off offset:1536 sc1
	v_pk_mul_f32 v[18:19], v[48:49], v[62:63] op_sel_hi:[1,0]
	v_pk_mul_f32 v[20:21], v[46:47], v[62:63] op_sel_hi:[1,0]
	s_waitcnt vmcnt(15)
	v_pk_add_f32 v[112:113], v[112:113], 1.0 op_sel_hi:[1,0]
	v_pk_add_f32 v[110:111], v[110:111], 1.0 op_sel_hi:[1,0]
	v_pk_mul_f32 v[22:23], v[52:53], v[62:63] op_sel_hi:[1,0]
	v_pk_mul_f32 v[24:25], v[50:51], v[62:63] op_sel_hi:[1,0]
	v_pk_mul_f32 v[26:27], v[56:57], v[62:63] op_sel_hi:[1,0]
	v_pk_mul_f32 v[28:29], v[54:55], v[62:63] op_sel_hi:[1,0]
	v_pk_mul_f32 v[30:31], v[60:61], v[62:63] op_sel_hi:[1,0]
	v_pk_mul_f32 v[32:33], v[58:59], v[62:63] op_sel_hi:[1,0]
	v_pk_mul_f32 v[20:21], v[2:3], v[20:21]
	v_pk_mul_f32 v[18:19], v[4:5], v[18:19]
	s_waitcnt vmcnt(14)
	v_pk_add_f32 v[116:117], v[116:117], 1.0 op_sel_hi:[1,0]
	v_pk_add_f32 v[114:115], v[114:115], 1.0 op_sel_hi:[1,0]
	s_waitcnt vmcnt(13)
	v_pk_add_f32 v[120:121], v[120:121], 1.0 op_sel_hi:[1,0]
	v_pk_add_f32 v[118:119], v[118:119], 1.0 op_sel_hi:[1,0]
	s_waitcnt vmcnt(12)
	v_pk_add_f32 v[124:125], v[124:125], 1.0 op_sel_hi:[1,0]
	v_pk_add_f32 v[122:123], v[122:123], 1.0 op_sel_hi:[1,0]
	v_pk_mul_f32 v[24:25], v[6:7], v[24:25]
	v_pk_mul_f32 v[22:23], v[8:9], v[22:23]
	v_pk_mul_f32 v[28:29], v[10:11], v[28:29]
	v_pk_mul_f32 v[26:27], v[12:13], v[26:27]
	v_pk_mul_f32 v[32:33], v[14:15], v[32:33]
	v_pk_mul_f32 v[30:31], v[16:17], v[30:31]
	v_pk_fma_f32 v[18:19], v[18:19], v[112:113], v[96:97]
	v_pk_fma_f32 v[20:21], v[20:21], v[110:111], v[94:95]
	v_lshl_add_u64 v[38:39], v[38:39], 0, s[22:23]
	v_pk_fma_f32 v[22:23], v[22:23], v[116:117], v[100:101]
	v_pk_fma_f32 v[24:25], v[24:25], v[114:115], v[98:99]
	v_pk_fma_f32 v[26:27], v[26:27], v[120:121], v[104:105]
	v_pk_fma_f32 v[28:29], v[28:29], v[118:119], v[102:103]
	v_pk_fma_f32 v[30:31], v[30:31], v[124:125], v[108:109]
	v_pk_fma_f32 v[32:33], v[32:33], v[122:123], v[106:107]
	v_cvt_pk_bf16_f32 v20, v20, v21
	v_cvt_pk_bf16_f32 v21, v18, v19
	v_cvt_pk_bf16_f32 v18, v24, v25
	v_cvt_pk_bf16_f32 v19, v22, v23
	v_cvt_pk_bf16_f32 v22, v28, v29
	v_cvt_pk_bf16_f32 v23, v26, v27
	v_cvt_pk_bf16_f32 v24, v32, v33
	v_cvt_pk_bf16_f32 v25, v30, v31
	global_store_dwordx2 v[126:127], v[20:21], off sc1
	global_store_dwordx2 v[126:127], v[18:19], off offset:512 sc1
	global_store_dwordx2 v[126:127], v[22:23], off offset:1024 sc1
	global_store_dwordx2 v[126:127], v[24:25], off offset:1536 sc1
	s_cbranch_scc1 .Lnpf2_done
.Lnpf2_b:
	s_lshr_b32 s43, s7, 11
	s_mul_i32 s26, s43, 0x1800
	s_ashr_i32 s27, s26, 31
	s_lshl_b64 s[26:27], s[26:27], 2
	s_add_u32 s26, s36, s26
	s_addc_u32 s27, s37, s27
	s_add_u32 s26, s26, 0x3000
	s_addc_u32 s27, s27, 0
	s_add_u32 s38, s26, 0x1000
	s_addc_u32 s39, s27, 0
	s_lshr_b32 s43, s40, 11
	global_load_dwordx4 v[62:65], v1, s[26:27]
	global_load_dwordx4 v[66:69], v1, s[26:27] offset:1024
	global_load_dwordx4 v[70:73], v1, s[26:27] offset:2048
	global_load_dwordx4 v[74:77], v1, s[26:27] offset:3072
	s_mul_i32 s26, s43, 0x1800
	s_ashr_i32 s27, s26, 31
	s_lshl_b64 s[26:27], s[26:27], 2
	global_load_dwordx4 v[78:81], v1, s[38:39]
	global_load_dwordx4 v[82:85], v42, s[38:39]
	global_load_dwordx4 v[86:89], v43, s[38:39]
	global_load_dwordx4 v[90:93], v44, s[38:39]
	s_add_u32 s26, s36, s26
	s_addc_u32 s27, s37, s27
	s_add_u32 s26, s26, 0x3000
	s_addc_u32 s27, s27, 0
	s_add_u32 s38, s26, 0x1000
	s_addc_u32 s39, s27, 0
	global_load_dwordx4 v[94:97], v1, s[26:27]
	global_load_dwordx4 v[98:101], v1, s[26:27] offset:1024
	global_load_dwordx4 v[102:105], v1, s[26:27] offset:2048
	global_load_dwordx4 v[106:109], v1, s[26:27] offset:3072
	global_load_dwordx4 v[110:113], v1, s[38:39]
	global_load_dwordx4 v[114:117], v42, s[38:39]
	global_load_dwordx4 v[118:121], v43, s[38:39]
	global_load_dwordx4 v[122:125], v44, s[38:39]
	s_lshl_b64 s[40:41], s[40:41], 11
	v_lshl_add_u64 v[126:127], v[36:37], 0, s[40:41]
	s_add_i32 s7, s7, s42
	v_lshl_add_u64 v[40:41], v[40:41], 0, s[28:29]
	s_cmpk_gt_i32 s7, 0x7fff
	s_cselect_b64 vcc, -1, 0
	s_add_i32 s43, s21, s7
	s_cmp_lt_i32 s43, 0x8000
	s_cselect_b32 s40, s43, s7
	s_ashr_i32 s41, s40, 31
	s_lshl_b64 s[38:39], s[40:41], 12
	v_lshl_add_u64 v[58:59], v[34:35], 0, s[38:39]
	v_cndmask_b32_e32 v202, v40, v200, vcc
	v_cndmask_b32_e32 v203, v41, v201, vcc
	v_cndmask_b32_e32 v58, v58, v200, vcc
	v_cndmask_b32_e32 v59, v59, v201, vcc
	global_load_dwordx4 v[30:33], v[202:203], off nt
	global_load_dwordx4 v[26:29], v[202:203], off offset:1024 nt
	global_load_dwordx4 v[22:25], v[202:203], off offset:2048 nt
	global_load_dwordx4 v[18:21], v[202:203], off offset:3072 nt
	global_load_dwordx4 v[46:49], v[58:59], off nt
	global_load_dwordx4 v[50:53], v[58:59], off offset:1024 nt
	global_load_dwordx4 v[54:57], v[58:59], off offset:2048 nt
	s_nop 0
	global_load_dwordx4 v[58:61], v[58:59], off offset:3072 nt
	s_cmpk_gt_i32 s7, 0x7fff
	s_waitcnt vmcnt(39)
	v_mul_f32_e32 v45, v181, v181
	v_mul_f32_e32 v128, v183, v183
	s_waitcnt vmcnt(38)
	v_mul_f32_e32 v129, v177, v177
	v_mul_f32_e32 v130, v179, v179
	s_waitcnt vmcnt(37)
	v_mul_f32_e32 v131, v173, v173
	v_mul_f32_e32 v132, v175, v175
	v_fmac_f32_e32 v45, v180, v180
	v_fmac_f32_e32 v128, v182, v182
	v_fmac_f32_e32 v129, v176, v176
	v_fmac_f32_e32 v130, v178, v178
	s_waitcnt vmcnt(36)
	v_mul_f32_e32 v133, v169, v169
	v_mul_f32_e32 v134, v171, v171
	v_fmac_f32_e32 v131, v172, v172
	v_fmac_f32_e32 v132, v174, v174
	v_add_f32_e32 v45, v45, v128
	v_add_f32_e32 v128, v129, v130
	v_fmac_f32_e32 v133, v168, v168
	v_fmac_f32_e32 v134, v170, v170
	v_add_f32_e32 v129, v131, v132
	v_add_f32_e32 v45, v45, v128
	v_add_f32_e32 v130, v133, v134
	v_add_f32_e32 v45, v45, v129
	v_add_f32_e32 v45, v45, v130
	s_waitcnt vmcnt(35)
	v_mul_f32_e32 v128, v185, v185
	v_mul_f32_e32 v129, v187, v187
	s_waitcnt vmcnt(34)
	v_mul_f32_e32 v130, v189, v189
	v_mul_f32_e32 v131, v191, v191
	v_add_f32_dpp v45, v45, v45 quad_perm:[1,0,3,2] row_mask:0xf bank_mask:0xf bound_ctrl:1
	s_waitcnt vmcnt(33)
	v_mul_f32_e32 v132, v193, v193
	v_mul_f32_e32 v133, v195, v195
	v_fmac_f32_e32 v128, v184, v184
	v_fmac_f32_e32 v129, v186, v186
	v_fmac_f32_e32 v130, v188, v188
	v_fmac_f32_e32 v131, v190, v190
	v_add_f32_dpp v45, v45, v45 quad_perm:[2,3,0,1] row_mask:0xf bank_mask:0xf bound_ctrl:1
	s_waitcnt vmcnt(32)
	v_mul_f32_e32 v134, v197, v197
	v_mul_f32_e32 v135, v199, v199
	v_fmac_f32_e32 v132, v192, v192
	v_fmac_f32_e32 v133, v194, v194
	v_add_f32_e32 v128, v128, v129
	v_add_f32_e32 v129, v130, v131
	v_add_f32_dpp v45, v45, v45 row_half_mirror row_mask:0xf bank_mask:0xf bound_ctrl:1
	v_fmac_f32_e32 v134, v196, v196
	v_fmac_f32_e32 v135, v198, v198
	v_add_f32_e32 v130, v132, v133
	v_add_f32_e32 v128, v128, v129
	v_add_f32_dpp v45, v45, v45 row_mirror row_mask:0xf bank_mask:0xf bound_ctrl:1
	v_add_f32_e32 v131, v134, v135
	v_add_f32_e32 v128, v128, v130
	v_mov_b32_e32 v129, v45
	v_add_f32_e32 v128, v128, v131
	s_nop 0
	v_permlane16_swap_b32_e32 v45, v129
	v_add_f32_e32 v45, v45, v129
	v_add_f32_dpp v128, v128, v128 quad_perm:[1,0,3,2] row_mask:0xf bank_mask:0xf bound_ctrl:1
	v_mov_b32_e32 v129, v45
	s_nop 1
	v_permlane32_swap_b32_e32 v45, v129
	v_add_f32_dpp v128, v128, v128 quad_perm:[2,3,0,1] row_mask:0xf bank_mask:0xf bound_ctrl:1
	v_add_f32_e32 v45, v45, v129
	v_fmamk_f32 v45, v45, 0x3a800000, v207
	v_add_f32_dpp v128, v128, v128 row_half_mirror row_mask:0xf bank_mask:0xf bound_ctrl:1
	s_waitcnt vmcnt(19)
	v_pk_add_f32 v[78:79], v[78:79], 1.0 op_sel_hi:[1,0]
	v_pk_add_f32 v[80:81], v[80:81], 1.0 op_sel_hi:[1,0]
	v_add_f32_dpp v129, v128, v128 row_mirror row_mask:0xf bank_mask:0xf bound_ctrl:1
	v_mov_b32_e32 v130, v129
	s_nop 1
	v_permlane16_swap_b32_e32 v129, v130
	v_rsq_f32_e32 v128, v45
	v_add_f32_e32 v45, v129, v130
	v_mov_b32_e32 v129, v45
	s_nop 1
	v_permlane32_swap_b32_e32 v45, v129
	v_add_f32_e32 v45, v45, v129
	v_pk_mul_f32 v[180:181], v[180:181], v[128:129] op_sel_hi:[1,0]
	v_fmamk_f32 v45, v45, 0x3a800000, v207
	v_pk_mul_f32 v[180:181], v[2:3], v[180:181]
	v_pk_mul_f32 v[182:183], v[182:183], v[128:129] op_sel_hi:[1,0]
	v_pk_mul_f32 v[170:171], v[170:171], v[128:129] op_sel_hi:[1,0]
	v_pk_mul_f32 v[168:169], v[168:169], v[128:129] op_sel_hi:[1,0]
	v_pk_fma_f32 v[180:181], v[78:79], v[180:181], v[62:63]
	v_rsq_f32_e32 v62, v45
	s_waitcnt vmcnt(16)
	v_pk_add_f32 v[92:93], v[92:93], 1.0 op_sel_hi:[1,0]
	v_pk_add_f32 v[90:91], v[90:91], 1.0 op_sel_hi:[1,0]
	v_pk_mul_f32 v[178:179], v[178:179], v[128:129] op_sel_hi:[1,0]
	v_pk_mul_f32 v[176:177], v[176:177], v[128:129] op_sel_hi:[1,0]
	v_pk_mul_f32 v[174:175], v[174:175], v[128:129] op_sel_hi:[1,0]
	v_pk_mul_f32 v[172:173], v[172:173], v[128:129] op_sel_hi:[1,0]
	v_pk_mul_f32 v[182:183], v[4:5], v[182:183]
	v_pk_mul_f32 v[168:169], v[14:15], v[168:169]
	v_pk_mul_f32 v[170:171], v[16:17], v[170:171]
	v_pk_add_f32 v[84:85], v[84:85], 1.0 op_sel_hi:[1,0]
	v_pk_add_f32 v[82:83], v[82:83], 1.0 op_sel_hi:[1,0]
	v_pk_add_f32 v[88:89], v[88:89], 1.0 op_sel_hi:[1,0]
	v_pk_add_f32 v[86:87], v[86:87], 1.0 op_sel_hi:[1,0]
	v_pk_mul_f32 v[176:177], v[6:7], v[176:177]
	v_pk_mul_f32 v[178:179], v[8:9], v[178:179]
	v_pk_mul_f32 v[172:173], v[10:11], v[172:173]
	v_pk_mul_f32 v[174:175], v[12:13], v[174:175]
	v_pk_fma_f32 v[182:183], v[80:81], v[182:183], v[64:65]
	v_pk_fma_f32 v[170:171], v[170:171], v[92:93], v[76:77]
	v_pk_fma_f32 v[168:169], v[168:169], v[90:91], v[74:75]
	v_pk_fma_f32 v[178:179], v[178:179], v[84:85], v[68:69]
	v_pk_fma_f32 v[176:177], v[176:177], v[82:83], v[66:67]
	v_pk_fma_f32 v[174:175], v[174:175], v[88:89], v[72:73]
	v_pk_fma_f32 v[172:173], v[172:173], v[86:87], v[70:71]
	v_cvt_pk_bf16_f32 v180, v180, v181
	v_cvt_pk_bf16_f32 v181, v182, v183
	v_cvt_pk_bf16_f32 v168, v168, v169
	v_cvt_pk_bf16_f32 v169, v170, v171
	v_cvt_pk_bf16_f32 v176, v176, v177
	v_cvt_pk_bf16_f32 v177, v178, v179
	v_cvt_pk_bf16_f32 v172, v172, v173
	v_cvt_pk_bf16_f32 v173, v174, v175
	global_store_dwordx2 v[38:39], v[180:181], off sc1
	global_store_dwordx2 v[38:39], v[176:177], off offset:512 sc1
	global_store_dwordx2 v[38:39], v[172:173], off offset:1024 sc1
	global_store_dwordx2 v[38:39], v[168:169], off offset:1536 sc1
	v_pk_mul_f32 v[168:169], v[186:187], v[62:63] op_sel_hi:[1,0]
	v_pk_mul_f32 v[170:171], v[184:185], v[62:63] op_sel_hi:[1,0]
	s_waitcnt vmcnt(15)
	v_pk_add_f32 v[112:113], v[112:113], 1.0 op_sel_hi:[1,0]
	v_pk_add_f32 v[110:111], v[110:111], 1.0 op_sel_hi:[1,0]
	v_pk_mul_f32 v[172:173], v[190:191], v[62:63] op_sel_hi:[1,0]
	v_pk_mul_f32 v[174:175], v[188:189], v[62:63] op_sel_hi:[1,0]
	v_pk_mul_f32 v[176:177], v[194:195], v[62:63] op_sel_hi:[1,0]
	v_pk_mul_f32 v[178:179], v[192:193], v[62:63] op_sel_hi:[1,0]
	v_pk_mul_f32 v[180:181], v[198:199], v[62:63] op_sel_hi:[1,0]
	v_pk_mul_f32 v[182:183], v[196:197], v[62:63] op_sel_hi:[1,0]
	v_pk_mul_f32 v[170:171], v[2:3], v[170:171]
	v_pk_mul_f32 v[168:169], v[4:5], v[168:169]
	s_waitcnt vmcnt(14)
	v_pk_add_f32 v[116:117], v[116:117], 1.0 op_sel_hi:[1,0]
	v_pk_add_f32 v[114:115], v[114:115], 1.0 op_sel_hi:[1,0]
	s_waitcnt vmcnt(13)
	v_pk_add_f32 v[120:121], v[120:121], 1.0 op_sel_hi:[1,0]
	v_pk_add_f32 v[118:119], v[118:119], 1.0 op_sel_hi:[1,0]
	s_waitcnt vmcnt(12)
	v_pk_add_f32 v[124:125], v[124:125], 1.0 op_sel_hi:[1,0]
	v_pk_add_f32 v[122:123], v[122:123], 1.0 op_sel_hi:[1,0]
	v_pk_mul_f32 v[174:175], v[6:7], v[174:175]
	v_pk_mul_f32 v[172:173], v[8:9], v[172:173]
	v_pk_mul_f32 v[178:179], v[10:11], v[178:179]
	v_pk_mul_f32 v[176:177], v[12:13], v[176:177]
	v_pk_mul_f32 v[182:183], v[14:15], v[182:183]
	v_pk_mul_f32 v[180:181], v[16:17], v[180:181]
	v_pk_fma_f32 v[168:169], v[168:169], v[112:113], v[96:97]
	v_pk_fma_f32 v[170:171], v[170:171], v[110:111], v[94:95]
	v_lshl_add_u64 v[38:39], v[38:39], 0, s[22:23]
	v_pk_fma_f32 v[172:173], v[172:173], v[116:117], v[100:101]
	v_pk_fma_f32 v[174:175], v[174:175], v[114:115], v[98:99]
	v_pk_fma_f32 v[176:177], v[176:177], v[120:121], v[104:105]
	v_pk_fma_f32 v[178:179], v[178:179], v[118:119], v[102:103]
	v_pk_fma_f32 v[180:181], v[180:181], v[124:125], v[108:109]
	v_pk_fma_f32 v[182:183], v[182:183], v[122:123], v[106:107]
	v_cvt_pk_bf16_f32 v170, v170, v171
	v_cvt_pk_bf16_f32 v171, v168, v169
	v_cvt_pk_bf16_f32 v168, v174, v175
	v_cvt_pk_bf16_f32 v169, v172, v173
	v_cvt_pk_bf16_f32 v172, v178, v179
	v_cvt_pk_bf16_f32 v173, v176, v177
	v_cvt_pk_bf16_f32 v174, v182, v183
	v_cvt_pk_bf16_f32 v175, v180, v181
	global_store_dwordx2 v[126:127], v[170:171], off sc1
	global_store_dwordx2 v[126:127], v[168:169], off offset:512 sc1
	global_store_dwordx2 v[126:127], v[172:173], off offset:1024 sc1
	global_store_dwordx2 v[126:127], v[174:175], off offset:1536 sc1
	s_cbranch_scc1 .Lnpf2_done
	s_branch .Lnpf2_a
.Lnpf2_done:
.LBB0_23:
	s_mov_b64 s[40:41], 0
	s_mov_b32 s31, -1
	s_mov_b64 s[28:29], -1
	s_mov_b32 s15, 0
	s_mov_b64 s[52:53], 0
	s_mov_b64 s[22:23], 0
	s_mov_b32 s38, 0
	s_mov_b32 s25, 0
	s_mov_b64 s[62:63], -1
	v_readlane_b32 s27, v255, 31

.Latt2_exit:
	v_lshlrev_b32_e32 v1, 4, v164
	v_add_u32_e32 v1, 0x14000, v1
	ds_read_b128 v[194:197], v1
	ds_read_b128 v[198:201], v1 offset:8192
	ds_read_b128 v[202:205], v1 offset:16384
	s_waitcnt lgkmcnt(0)
	s_branch .LBB0_44
	s_nop 0
	s_nop 0
	s_nop 0
	s_nop 0
	s_nop 0
	s_nop 0
	s_nop 0
	s_nop 0
	s_nop 0
	s_nop 0
	s_nop 0
	s_nop 0
	s_nop 0
	s_nop 0
	s_nop 0
	s_nop 0
	s_nop 0
	s_nop 0
	s_nop 0
	s_nop 0
	s_nop 0
	s_nop 0
	s_nop 0
	s_nop 0
	s_nop 0
	s_nop 0
	s_nop 0
	s_nop 0
	s_nop 0
	s_nop 0
	s_nop 0
	s_nop 0
	s_nop 0
	s_nop 0
	s_nop 0
	s_nop 0
	s_nop 0
	s_nop 0
	s_nop 0
	s_nop 0
	s_nop 0
	s_nop 0
	s_nop 0
	s_nop 0
	s_nop 0
	s_nop 0
	s_nop 0
	s_nop 0
	s_nop 0
	s_nop 0
	s_nop 0
	s_nop 0
	s_nop 0
	s_nop 0
	s_nop 0
	s_nop 0
	s_nop 0

.LBB0_193:
	s_cmp_gt_i32 s27, 0
	s_mov_b64 s[8:9], -1
	s_cbranch_scc0 .LBB0_198
	s_cmpk_gt_i32 s6, 0x7fff
	s_cbranch_scc1 .LBB0_197
	s_load_dwordx2 s[8:9], s[0:1], 0x28
	s_load_dwordx2 s[24:25], s[0:1], 0x0
	v_lshlrev_b32_e32 v18, 4, v227
	s_add_u32 s22, s36, 0x13600000
	s_addc_u32 s23, s37, 0
	s_waitcnt lgkmcnt(0)
	v_mov_b32_e32 v200, v18
	v_mov_b32_e32 v201, v0
	v_lshl_add_u64 v[200:201], s[8:9], 0, v[200:201]
	s_ashr_i32 s7, s6, 31
	s_lshl_b32 s8, s30, 4
	v_lshlrev_b32_e32 v28, 3, v227
	v_mov_b32_e32 v29, v0
	s_lshl_b64 s[26:27], s[6:7], 11
	v_lshl_add_u64 v[36:37], s[22:23], 0, v[28:29]
	s_add_u32 s22, s22, s26
	s_addc_u32 s23, s23, s27
	s_ashr_i32 s9, s8, 31
	v_mov_b32_e32 v19, v0
	v_lshl_add_u64 v[38:39], s[22:23], 0, v[28:29]
	s_lshl_b64 s[22:23], s[8:9], 11
	s_lshl_b64 s[26:27], s[6:7], 12
	v_lshl_add_u64 v[34:35], s[24:25], 0, v[18:19]
	v_lshlrev_b32_e32 v20, 2, v227
	s_add_u32 s24, s24, s26
	v_or_b32_e32 v22, 0x100, v20
	v_or_b32_e32 v24, 0x200, v20
	v_or_b32_e32 v26, 0x300, v20
	s_addc_u32 s25, s25, s27
	v_lshl_add_u64 v[40:41], s[24:25], 0, v[18:19]
	s_lshl_b64 s[28:29], s[8:9], 12
	v_lshlrev_b32_e32 v1, 2, v20
	v_lshlrev_b32_e32 v42, 2, v22
	v_lshlrev_b32_e32 v43, 2, v24
	v_lshlrev_b32_e32 v44, 2, v26
	s_mov_b32 s7, s6
	global_load_dwordx4 v[30:33], v[40:41], off nt
	global_load_dwordx4 v[26:29], v[40:41], off offset:1024 nt
	global_load_dwordx4 v[22:25], v[40:41], off offset:2048 nt
	global_load_dwordx4 v[18:21], v[40:41], off offset:3072 nt
	s_add_i32 s9, s21, s7
	s_cmp_lt_i32 s9, 0x8000
	s_cselect_b32 s24, s9, s7
	s_ashr_i32 s25, s24, 31
	s_lshl_b64 s[38:39], s[24:25], 12
	v_lshl_add_u64 v[58:59], v[34:35], 0, s[38:39]
	global_load_dwordx4 v[46:49], v[58:59], off nt
	global_load_dwordx4 v[50:53], v[58:59], off offset:1024 nt
	global_load_dwordx4 v[54:57], v[58:59], off offset:2048 nt
	s_nop 0
	global_load_dwordx4 v[58:61], v[58:59], off offset:3072 nt
	global_load_dwordx4 v[2:5], v[200:201], off
	global_load_dwordx4 v[6:9], v[200:201], off offset:1024
	global_load_dwordx4 v[10:13], v[200:201], off offset:2048
	global_load_dwordx4 v[14:17], v[200:201], off offset:3072
	global_load_dwordx4 v[2:5], v[200:201], off
	global_load_dwordx4 v[6:9], v[200:201], off offset:1024
	global_load_dwordx4 v[10:13], v[200:201], off offset:2048
	global_load_dwordx4 v[14:17], v[200:201], off offset:3072
.Lnpf1_a:
	s_lshr_b32 s9, s7, 11
	s_mul_i32 s26, s9, 0x1800
	s_ashr_i32 s27, s26, 31
	s_lshl_b64 s[26:27], s[26:27], 2
	s_add_u32 s26, s36, s26
	s_addc_u32 s27, s37, s27
	s_add_u32 s38, s26, 0x1000
	s_addc_u32 s39, s27, 0
	s_lshr_b32 s9, s24, 11
	global_load_dwordx4 v[62:65], v1, s[26:27]
	global_load_dwordx4 v[66:69], v1, s[26:27] offset:1024
	global_load_dwordx4 v[70:73], v1, s[26:27] offset:2048
	global_load_dwordx4 v[74:77], v1, s[26:27] offset:3072
	s_mul_i32 s26, s9, 0x1800
	s_ashr_i32 s27, s26, 31
	s_lshl_b64 s[26:27], s[26:27], 2
	global_load_dwordx4 v[78:81], v1, s[38:39]
	global_load_dwordx4 v[82:85], v42, s[38:39]
	global_load_dwordx4 v[86:89], v43, s[38:39]
	global_load_dwordx4 v[90:93], v44, s[38:39]
	s_add_u32 s26, s36, s26
	s_addc_u32 s27, s37, s27
	s_add_u32 s38, s26, 0x1000
	s_addc_u32 s39, s27, 0
	global_load_dwordx4 v[94:97], v1, s[26:27]
	global_load_dwordx4 v[98:101], v1, s[26:27] offset:1024
	global_load_dwordx4 v[102:105], v1, s[26:27] offset:2048
	global_load_dwordx4 v[106:109], v1, s[26:27] offset:3072
	global_load_dwordx4 v[110:113], v1, s[38:39]
	global_load_dwordx4 v[114:117], v42, s[38:39]
	global_load_dwordx4 v[118:121], v43, s[38:39]
	global_load_dwordx4 v[122:125], v44, s[38:39]
	s_lshl_b64 s[24:25], s[24:25], 11
	v_lshl_add_u64 v[126:127], v[36:37], 0, s[24:25]
	s_add_i32 s7, s7, s8
	v_lshl_add_u64 v[40:41], v[40:41], 0, s[28:29]
	s_cmpk_gt_i32 s7, 0x7fff
	s_cselect_b64 vcc, -1, 0
	s_add_i32 s9, s21, s7
	s_cmp_lt_i32 s9, 0x8000
	s_cselect_b32 s24, s9, s7
	s_ashr_i32 s25, s24, 31
	s_lshl_b64 s[38:39], s[24:25], 12
	v_lshl_add_u64 v[196:197], v[34:35], 0, s[38:39]
	v_cndmask_b32_e32 v202, v40, v200, vcc
	v_cndmask_b32_e32 v203, v41, v201, vcc
	v_cndmask_b32_e32 v196, v196, v200, vcc
	v_cndmask_b32_e32 v197, v197, v201, vcc
	global_load_dwordx4 v[180:183], v[202:203], off nt
	global_load_dwordx4 v[176:179], v[202:203], off offset:1024 nt
	global_load_dwordx4 v[172:175], v[202:203], off offset:2048 nt
	global_load_dwordx4 v[168:171], v[202:203], off offset:3072 nt
	global_load_dwordx4 v[184:187], v[196:197], off nt
	global_load_dwordx4 v[188:191], v[196:197], off offset:1024 nt
	global_load_dwordx4 v[192:195], v[196:197], off offset:2048 nt
	s_nop 0
	global_load_dwordx4 v[196:199], v[196:197], off offset:3072 nt
	s_cmpk_gt_i32 s7, 0x7fff
	s_waitcnt vmcnt(39)
	v_mul_f32_e32 v45, v31, v31
	v_mul_f32_e32 v128, v33, v33
	s_waitcnt vmcnt(38)
	v_mul_f32_e32 v129, v27, v27
	v_mul_f32_e32 v130, v29, v29
	s_waitcnt vmcnt(37)
	v_mul_f32_e32 v131, v23, v23
	v_mul_f32_e32 v132, v25, v25
	v_fmac_f32_e32 v45, v30, v30
	v_fmac_f32_e32 v128, v32, v32
	v_fmac_f32_e32 v129, v26, v26
	v_fmac_f32_e32 v130, v28, v28
	s_waitcnt vmcnt(36)
	v_mul_f32_e32 v133, v19, v19
	v_mul_f32_e32 v134, v21, v21
	v_fmac_f32_e32 v131, v22, v22
	v_fmac_f32_e32 v132, v24, v24
	v_add_f32_e32 v45, v45, v128
	v_add_f32_e32 v128, v129, v130
	v_fmac_f32_e32 v133, v18, v18
	v_fmac_f32_e32 v134, v20, v20
	v_add_f32_e32 v129, v131, v132
	v_add_f32_e32 v45, v45, v128
	v_add_f32_e32 v130, v133, v134
	v_add_f32_e32 v45, v45, v129
	v_add_f32_e32 v45, v45, v130
	s_waitcnt vmcnt(35)
	v_mul_f32_e32 v128, v47, v47
	v_mul_f32_e32 v129, v49, v49
	s_waitcnt vmcnt(34)
	v_mul_f32_e32 v130, v51, v51
	v_mul_f32_e32 v131, v53, v53
	v_add_f32_dpp v45, v45, v45 quad_perm:[1,0,3,2] row_mask:0xf bank_mask:0xf bound_ctrl:1
	s_waitcnt vmcnt(33)
	v_mul_f32_e32 v132, v55, v55
	v_mul_f32_e32 v133, v57, v57
	v_fmac_f32_e32 v128, v46, v46
	v_fmac_f32_e32 v129, v48, v48
	v_fmac_f32_e32 v130, v50, v50
	v_fmac_f32_e32 v131, v52, v52
	v_add_f32_dpp v45, v45, v45 quad_perm:[2,3,0,1] row_mask:0xf bank_mask:0xf bound_ctrl:1
	s_waitcnt vmcnt(32)
	v_mul_f32_e32 v134, v59, v59
	v_mul_f32_e32 v135, v61, v61
	v_fmac_f32_e32 v132, v54, v54
	v_fmac_f32_e32 v133, v56, v56
	v_add_f32_e32 v128, v128, v129
	v_add_f32_e32 v129, v130, v131
	v_add_f32_dpp v45, v45, v45 row_half_mirror row_mask:0xf bank_mask:0xf bound_ctrl:1
	v_fmac_f32_e32 v134, v58, v58
	v_fmac_f32_e32 v135, v60, v60
	v_add_f32_e32 v130, v132, v133
	v_add_f32_e32 v128, v128, v129
	v_add_f32_dpp v45, v45, v45 row_mirror row_mask:0xf bank_mask:0xf bound_ctrl:1
	v_add_f32_e32 v131, v134, v135
	v_add_f32_e32 v128, v128, v130
	v_mov_b32_e32 v129, v45
	v_add_f32_e32 v128, v128, v131
	s_nop 0
	v_permlane16_swap_b32_e32 v45, v129
	v_add_f32_e32 v45, v45, v129
	v_add_f32_dpp v128, v128, v128 quad_perm:[1,0,3,2] row_mask:0xf bank_mask:0xf bound_ctrl:1
	v_mov_b32_e32 v129, v45
	s_nop 1
	v_permlane32_swap_b32_e32 v45, v129
	v_add_f32_dpp v128, v128, v128 quad_perm:[2,3,0,1] row_mask:0xf bank_mask:0xf bound_ctrl:1
	v_add_f32_e32 v45, v45, v129
	v_fmamk_f32 v45, v45, 0x3a800000, v207
	v_add_f32_dpp v128, v128, v128 row_half_mirror row_mask:0xf bank_mask:0xf bound_ctrl:1
	s_waitcnt vmcnt(19)
	v_pk_add_f32 v[78:79], v[78:79], 1.0 op_sel_hi:[1,0]
	v_pk_add_f32 v[80:81], v[80:81], 1.0 op_sel_hi:[1,0]
	v_add_f32_dpp v129, v128, v128 row_mirror row_mask:0xf bank_mask:0xf bound_ctrl:1
	v_mov_b32_e32 v130, v129
	s_nop 1
	v_permlane16_swap_b32_e32 v129, v130
	v_rsq_f32_e32 v128, v45
	v_add_f32_e32 v45, v129, v130
	v_mov_b32_e32 v129, v45
	s_nop 1
	v_permlane32_swap_b32_e32 v45, v129
	v_add_f32_e32 v45, v45, v129
	v_pk_mul_f32 v[30:31], v[30:31], v[128:129] op_sel_hi:[1,0]
	v_fmamk_f32 v45, v45, 0x3a800000, v207
	v_pk_mul_f32 v[30:31], v[2:3], v[30:31]
	v_pk_mul_f32 v[32:33], v[32:33], v[128:129] op_sel_hi:[1,0]
	v_pk_mul_f32 v[20:21], v[20:21], v[128:129] op_sel_hi:[1,0]
	v_pk_mul_f32 v[18:19], v[18:19], v[128:129] op_sel_hi:[1,0]
	v_pk_fma_f32 v[30:31], v[78:79], v[30:31], v[62:63]
	v_rsq_f32_e32 v62, v45
	s_waitcnt vmcnt(16)
	v_pk_add_f32 v[92:93], v[92:93], 1.0 op_sel_hi:[1,0]
	v_pk_add_f32 v[90:91], v[90:91], 1.0 op_sel_hi:[1,0]
	v_pk_mul_f32 v[28:29], v[28:29], v[128:129] op_sel_hi:[1,0]
	v_pk_mul_f32 v[26:27], v[26:27], v[128:129] op_sel_hi:[1,0]
	v_pk_mul_f32 v[24:25], v[24:25], v[128:129] op_sel_hi:[1,0]
	v_pk_mul_f32 v[22:23], v[22:23], v[128:129] op_sel_hi:[1,0]
	v_pk_mul_f32 v[32:33], v[4:5], v[32:33]
	v_pk_mul_f32 v[18:19], v[14:15], v[18:19]
	v_pk_mul_f32 v[20:21], v[16:17], v[20:21]
	v_pk_add_f32 v[84:85], v[84:85], 1.0 op_sel_hi:[1,0]
	v_pk_add_f32 v[82:83], v[82:83], 1.0 op_sel_hi:[1,0]
	v_pk_add_f32 v[88:89], v[88:89], 1.0 op_sel_hi:[1,0]
	v_pk_add_f32 v[86:87], v[86:87], 1.0 op_sel_hi:[1,0]
	v_pk_mul_f32 v[26:27], v[6:7], v[26:27]
	v_pk_mul_f32 v[28:29], v[8:9], v[28:29]
	v_pk_mul_f32 v[22:23], v[10:11], v[22:23]
	v_pk_mul_f32 v[24:25], v[12:13], v[24:25]
	v_pk_fma_f32 v[32:33], v[80:81], v[32:33], v[64:65]
	v_pk_fma_f32 v[20:21], v[20:21], v[92:93], v[76:77]
	v_pk_fma_f32 v[18:19], v[18:19], v[90:91], v[74:75]
	v_pk_fma_f32 v[28:29], v[28:29], v[84:85], v[68:69]
	v_pk_fma_f32 v[26:27], v[26:27], v[82:83], v[66:67]
	v_pk_fma_f32 v[24:25], v[24:25], v[88:89], v[72:73]
	v_pk_fma_f32 v[22:23], v[22:23], v[86:87], v[70:71]
	v_cvt_pk_bf16_f32 v30, v30, v31
	v_cvt_pk_bf16_f32 v31, v32, v33
	v_cvt_pk_bf16_f32 v18, v18, v19
	v_cvt_pk_bf16_f32 v19, v20, v21
	v_cvt_pk_bf16_f32 v26, v26, v27
	v_cvt_pk_bf16_f32 v27, v28, v29
	v_cvt_pk_bf16_f32 v22, v22, v23
	v_cvt_pk_bf16_f32 v23, v24, v25
	global_store_dwordx2 v[38:39], v[30:31], off sc1
	global_store_dwordx2 v[38:39], v[26:27], off offset:512 sc1
	global_store_dwordx2 v[38:39], v[22:23], off offset:1024 sc1
	global_store_dwordx2 v[38:39], v[18:19], off offset:1536 sc1
	v_pk_mul_f32 v[18:19], v[48:49], v[62:63] op_sel_hi:[1,0]
	v_pk_mul_f32 v[20:21], v[46:47], v[62:63] op_sel_hi:[1,0]
	s_waitcnt vmcnt(15)
	v_pk_add_f32 v[112:113], v[112:113], 1.0 op_sel_hi:[1,0]
	v_pk_add_f32 v[110:111], v[110:111], 1.0 op_sel_hi:[1,0]
	v_pk_mul_f32 v[22:23], v[52:53], v[62:63] op_sel_hi:[1,0]
	v_pk_mul_f32 v[24:25], v[50:51], v[62:63] op_sel_hi:[1,0]
	v_pk_mul_f32 v[26:27], v[56:57], v[62:63] op_sel_hi:[1,0]
	v_pk_mul_f32 v[28:29], v[54:55], v[62:63] op_sel_hi:[1,0]
	v_pk_mul_f32 v[30:31], v[60:61], v[62:63] op_sel_hi:[1,0]
	v_pk_mul_f32 v[32:33], v[58:59], v[62:63] op_sel_hi:[1,0]
	v_pk_mul_f32 v[20:21], v[2:3], v[20:21]
	v_pk_mul_f32 v[18:19], v[4:5], v[18:19]
	s_waitcnt vmcnt(14)
	v_pk_add_f32 v[116:117], v[116:117], 1.0 op_sel_hi:[1,0]
	v_pk_add_f32 v[114:115], v[114:115], 1.0 op_sel_hi:[1,0]
	s_waitcnt vmcnt(13)
	v_pk_add_f32 v[120:121], v[120:121], 1.0 op_sel_hi:[1,0]
	v_pk_add_f32 v[118:119], v[118:119], 1.0 op_sel_hi:[1,0]
	s_waitcnt vmcnt(12)
	v_pk_add_f32 v[124:125], v[124:125], 1.0 op_sel_hi:[1,0]
	v_pk_add_f32 v[122:123], v[122:123], 1.0 op_sel_hi:[1,0]
	v_pk_mul_f32 v[24:25], v[6:7], v[24:25]
	v_pk_mul_f32 v[22:23], v[8:9], v[22:23]
	v_pk_mul_f32 v[28:29], v[10:11], v[28:29]
	v_pk_mul_f32 v[26:27], v[12:13], v[26:27]
	v_pk_mul_f32 v[32:33], v[14:15], v[32:33]
	v_pk_mul_f32 v[30:31], v[16:17], v[30:31]
	v_pk_fma_f32 v[18:19], v[18:19], v[112:113], v[96:97]
	v_pk_fma_f32 v[20:21], v[20:21], v[110:111], v[94:95]
	v_lshl_add_u64 v[38:39], v[38:39], 0, s[22:23]
	v_pk_fma_f32 v[22:23], v[22:23], v[116:117], v[100:101]
	v_pk_fma_f32 v[24:25], v[24:25], v[114:115], v[98:99]
	v_pk_fma_f32 v[26:27], v[26:27], v[120:121], v[104:105]
	v_pk_fma_f32 v[28:29], v[28:29], v[118:119], v[102:103]
	v_pk_fma_f32 v[30:31], v[30:31], v[124:125], v[108:109]
	v_pk_fma_f32 v[32:33], v[32:33], v[122:123], v[106:107]
	v_cvt_pk_bf16_f32 v20, v20, v21
	v_cvt_pk_bf16_f32 v21, v18, v19
	v_cvt_pk_bf16_f32 v18, v24, v25
	v_cvt_pk_bf16_f32 v19, v22, v23
	v_cvt_pk_bf16_f32 v22, v28, v29
	v_cvt_pk_bf16_f32 v23, v26, v27
	v_cvt_pk_bf16_f32 v24, v32, v33
	v_cvt_pk_bf16_f32 v25, v30, v31
	global_store_dwordx2 v[126:127], v[20:21], off sc1
	global_store_dwordx2 v[126:127], v[18:19], off offset:512 sc1
	global_store_dwordx2 v[126:127], v[22:23], off offset:1024 sc1
	global_store_dwordx2 v[126:127], v[24:25], off offset:1536 sc1
	s_cbranch_scc1 .Lnpf1_done
.Lnpf1_b:
	s_lshr_b32 s9, s7, 11
	s_mul_i32 s26, s9, 0x1800
	s_ashr_i32 s27, s26, 31
	s_lshl_b64 s[26:27], s[26:27], 2
	s_add_u32 s26, s36, s26
	s_addc_u32 s27, s37, s27
	s_add_u32 s38, s26, 0x1000
	s_addc_u32 s39, s27, 0
	s_lshr_b32 s9, s24, 11
	global_load_dwordx4 v[62:65], v1, s[26:27]
	global_load_dwordx4 v[66:69], v1, s[26:27] offset:1024
	global_load_dwordx4 v[70:73], v1, s[26:27] offset:2048
	global_load_dwordx4 v[74:77], v1, s[26:27] offset:3072
	s_mul_i32 s26, s9, 0x1800
	s_ashr_i32 s27, s26, 31
	s_lshl_b64 s[26:27], s[26:27], 2
	global_load_dwordx4 v[78:81], v1, s[38:39]
	global_load_dwordx4 v[82:85], v42, s[38:39]
	global_load_dwordx4 v[86:89], v43, s[38:39]
	global_load_dwordx4 v[90:93], v44, s[38:39]
	s_add_u32 s26, s36, s26
	s_addc_u32 s27, s37, s27
	s_add_u32 s38, s26, 0x1000
	s_addc_u32 s39, s27, 0
	global_load_dwordx4 v[94:97], v1, s[26:27]
	global_load_dwordx4 v[98:101], v1, s[26:27] offset:1024
	global_load_dwordx4 v[102:105], v1, s[26:27] offset:2048
	global_load_dwordx4 v[106:109], v1, s[26:27] offset:3072
	global_load_dwordx4 v[110:113], v1, s[38:39]
	global_load_dwordx4 v[114:117], v42, s[38:39]
	global_load_dwordx4 v[118:121], v43, s[38:39]
	global_load_dwordx4 v[122:125], v44, s[38:39]
	s_lshl_b64 s[24:25], s[24:25], 11
	v_lshl_add_u64 v[126:127], v[36:37], 0, s[24:25]
	s_add_i32 s7, s7, s8
	v_lshl_add_u64 v[40:41], v[40:41], 0, s[28:29]
	s_cmpk_gt_i32 s7, 0x7fff
	s_cselect_b64 vcc, -1, 0
	s_add_i32 s9, s21, s7
	s_cmp_lt_i32 s9, 0x8000
	s_cselect_b32 s24, s9, s7
	s_ashr_i32 s25, s24, 31
	s_lshl_b64 s[38:39], s[24:25], 12
	v_lshl_add_u64 v[58:59], v[34:35], 0, s[38:39]
	v_cndmask_b32_e32 v202, v40, v200, vcc
	v_cndmask_b32_e32 v203, v41, v201, vcc
	v_cndmask_b32_e32 v58, v58, v200, vcc
	v_cndmask_b32_e32 v59, v59, v201, vcc
	global_load_dwordx4 v[30:33], v[202:203], off nt
	global_load_dwordx4 v[26:29], v[202:203], off offset:1024 nt
	global_load_dwordx4 v[22:25], v[202:203], off offset:2048 nt
	global_load_dwordx4 v[18:21], v[202:203], off offset:3072 nt
	global_load_dwordx4 v[46:49], v[58:59], off nt
	global_load_dwordx4 v[50:53], v[58:59], off offset:1024 nt
	global_load_dwordx4 v[54:57], v[58:59], off offset:2048 nt
	s_nop 0
	global_load_dwordx4 v[58:61], v[58:59], off offset:3072 nt
	s_cmpk_gt_i32 s7, 0x7fff
	s_waitcnt vmcnt(39)
	v_mul_f32_e32 v45, v181, v181
	v_mul_f32_e32 v128, v183, v183
	s_waitcnt vmcnt(38)
	v_mul_f32_e32 v129, v177, v177
	v_mul_f32_e32 v130, v179, v179
	s_waitcnt vmcnt(37)
	v_mul_f32_e32 v131, v173, v173
	v_mul_f32_e32 v132, v175, v175
	v_fmac_f32_e32 v45, v180, v180
	v_fmac_f32_e32 v128, v182, v182
	v_fmac_f32_e32 v129, v176, v176
	v_fmac_f32_e32 v130, v178, v178
	s_waitcnt vmcnt(36)
	v_mul_f32_e32 v133, v169, v169
	v_mul_f32_e32 v134, v171, v171
	v_fmac_f32_e32 v131, v172, v172
	v_fmac_f32_e32 v132, v174, v174
	v_add_f32_e32 v45, v45, v128
	v_add_f32_e32 v128, v129, v130
	v_fmac_f32_e32 v133, v168, v168
	v_fmac_f32_e32 v134, v170, v170
	v_add_f32_e32 v129, v131, v132
	v_add_f32_e32 v45, v45, v128
	v_add_f32_e32 v130, v133, v134
	v_add_f32_e32 v45, v45, v129
	v_add_f32_e32 v45, v45, v130
	s_waitcnt vmcnt(35)
	v_mul_f32_e32 v128, v185, v185
	v_mul_f32_e32 v129, v187, v187
	s_waitcnt vmcnt(34)
	v_mul_f32_e32 v130, v189, v189
	v_mul_f32_e32 v131, v191, v191
	v_add_f32_dpp v45, v45, v45 quad_perm:[1,0,3,2] row_mask:0xf bank_mask:0xf bound_ctrl:1
	s_waitcnt vmcnt(33)
	v_mul_f32_e32 v132, v193, v193
	v_mul_f32_e32 v133, v195, v195
	v_fmac_f32_e32 v128, v184, v184
	v_fmac_f32_e32 v129, v186, v186
	v_fmac_f32_e32 v130, v188, v188
	v_fmac_f32_e32 v131, v190, v190
	v_add_f32_dpp v45, v45, v45 quad_perm:[2,3,0,1] row_mask:0xf bank_mask:0xf bound_ctrl:1
	s_waitcnt vmcnt(32)
	v_mul_f32_e32 v134, v197, v197
	v_mul_f32_e32 v135, v199, v199
	v_fmac_f32_e32 v132, v192, v192
	v_fmac_f32_e32 v133, v194, v194
	v_add_f32_e32 v128, v128, v129
	v_add_f32_e32 v129, v130, v131
	v_add_f32_dpp v45, v45, v45 row_half_mirror row_mask:0xf bank_mask:0xf bound_ctrl:1
	v_fmac_f32_e32 v134, v196, v196
	v_fmac_f32_e32 v135, v198, v198
	v_add_f32_e32 v130, v132, v133
	v_add_f32_e32 v128, v128, v129
	v_add_f32_dpp v45, v45, v45 row_mirror row_mask:0xf bank_mask:0xf bound_ctrl:1
	v_add_f32_e32 v131, v134, v135
	v_add_f32_e32 v128, v128, v130
	v_mov_b32_e32 v129, v45
	v_add_f32_e32 v128, v128, v131
	s_nop 0
	v_permlane16_swap_b32_e32 v45, v129
	v_add_f32_e32 v45, v45, v129
	v_add_f32_dpp v128, v128, v128 quad_perm:[1,0,3,2] row_mask:0xf bank_mask:0xf bound_ctrl:1
	v_mov_b32_e32 v129, v45
	s_nop 1
	v_permlane32_swap_b32_e32 v45, v129
	v_add_f32_dpp v128, v128, v128 quad_perm:[2,3,0,1] row_mask:0xf bank_mask:0xf bound_ctrl:1
	v_add_f32_e32 v45, v45, v129
	v_fmamk_f32 v45, v45, 0x3a800000, v207
	v_add_f32_dpp v128, v128, v128 row_half_mirror row_mask:0xf bank_mask:0xf bound_ctrl:1
	s_waitcnt vmcnt(19)
	v_pk_add_f32 v[78:79], v[78:79], 1.0 op_sel_hi:[1,0]
	v_pk_add_f32 v[80:81], v[80:81], 1.0 op_sel_hi:[1,0]
	v_add_f32_dpp v129, v128, v128 row_mirror row_mask:0xf bank_mask:0xf bound_ctrl:1
	v_mov_b32_e32 v130, v129
	s_nop 1
	v_permlane16_swap_b32_e32 v129, v130
	v_rsq_f32_e32 v128, v45
	v_add_f32_e32 v45, v129, v130
	v_mov_b32_e32 v129, v45
	s_nop 1
	v_permlane32_swap_b32_e32 v45, v129
	v_add_f32_e32 v45, v45, v129
	v_pk_mul_f32 v[180:181], v[180:181], v[128:129] op_sel_hi:[1,0]
	v_fmamk_f32 v45, v45, 0x3a800000, v207
	v_pk_mul_f32 v[180:181], v[2:3], v[180:181]
	v_pk_mul_f32 v[182:183], v[182:183], v[128:129] op_sel_hi:[1,0]
	v_pk_mul_f32 v[170:171], v[170:171], v[128:129] op_sel_hi:[1,0]
	v_pk_mul_f32 v[168:169], v[168:169], v[128:129] op_sel_hi:[1,0]
	v_pk_fma_f32 v[180:181], v[78:79], v[180:181], v[62:63]
	v_rsq_f32_e32 v62, v45
	s_waitcnt vmcnt(16)
	v_pk_add_f32 v[92:93], v[92:93], 1.0 op_sel_hi:[1,0]
	v_pk_add_f32 v[90:91], v[90:91], 1.0 op_sel_hi:[1,0]
	v_pk_mul_f32 v[178:179], v[178:179], v[128:129] op_sel_hi:[1,0]
	v_pk_mul_f32 v[176:177], v[176:177], v[128:129] op_sel_hi:[1,0]
	v_pk_mul_f32 v[174:175], v[174:175], v[128:129] op_sel_hi:[1,0]
	v_pk_mul_f32 v[172:173], v[172:173], v[128:129] op_sel_hi:[1,0]
	v_pk_mul_f32 v[182:183], v[4:5], v[182:183]
	v_pk_mul_f32 v[168:169], v[14:15], v[168:169]
	v_pk_mul_f32 v[170:171], v[16:17], v[170:171]
	v_pk_add_f32 v[84:85], v[84:85], 1.0 op_sel_hi:[1,0]
	v_pk_add_f32 v[82:83], v[82:83], 1.0 op_sel_hi:[1,0]
	v_pk_add_f32 v[88:89], v[88:89], 1.0 op_sel_hi:[1,0]
	v_pk_add_f32 v[86:87], v[86:87], 1.0 op_sel_hi:[1,0]
	v_pk_mul_f32 v[176:177], v[6:7], v[176:177]
	v_pk_mul_f32 v[178:179], v[8:9], v[178:179]
	v_pk_mul_f32 v[172:173], v[10:11], v[172:173]
	v_pk_mul_f32 v[174:175], v[12:13], v[174:175]
	v_pk_fma_f32 v[182:183], v[80:81], v[182:183], v[64:65]
	v_pk_fma_f32 v[170:171], v[170:171], v[92:93], v[76:77]
	v_pk_fma_f32 v[168:169], v[168:169], v[90:91], v[74:75]
	v_pk_fma_f32 v[178:179], v[178:179], v[84:85], v[68:69]
	v_pk_fma_f32 v[176:177], v[176:177], v[82:83], v[66:67]
	v_pk_fma_f32 v[174:175], v[174:175], v[88:89], v[72:73]
	v_pk_fma_f32 v[172:173], v[172:173], v[86:87], v[70:71]
	v_cvt_pk_bf16_f32 v180, v180, v181
	v_cvt_pk_bf16_f32 v181, v182, v183
	v_cvt_pk_bf16_f32 v168, v168, v169
	v_cvt_pk_bf16_f32 v169, v170, v171
	v_cvt_pk_bf16_f32 v176, v176, v177
	v_cvt_pk_bf16_f32 v177, v178, v179
	v_cvt_pk_bf16_f32 v172, v172, v173
	v_cvt_pk_bf16_f32 v173, v174, v175
	global_store_dwordx2 v[38:39], v[180:181], off sc1
	global_store_dwordx2 v[38:39], v[176:177], off offset:512 sc1
	global_store_dwordx2 v[38:39], v[172:173], off offset:1024 sc1
	global_store_dwordx2 v[38:39], v[168:169], off offset:1536 sc1
	v_pk_mul_f32 v[168:169], v[186:187], v[62:63] op_sel_hi:[1,0]
	v_pk_mul_f32 v[170:171], v[184:185], v[62:63] op_sel_hi:[1,0]
	s_waitcnt vmcnt(15)
	v_pk_add_f32 v[112:113], v[112:113], 1.0 op_sel_hi:[1,0]
	v_pk_add_f32 v[110:111], v[110:111], 1.0 op_sel_hi:[1,0]
	v_pk_mul_f32 v[172:173], v[190:191], v[62:63] op_sel_hi:[1,0]
	v_pk_mul_f32 v[174:175], v[188:189], v[62:63] op_sel_hi:[1,0]
	v_pk_mul_f32 v[176:177], v[194:195], v[62:63] op_sel_hi:[1,0]
	v_pk_mul_f32 v[178:179], v[192:193], v[62:63] op_sel_hi:[1,0]
	v_pk_mul_f32 v[180:181], v[198:199], v[62:63] op_sel_hi:[1,0]
	v_pk_mul_f32 v[182:183], v[196:197], v[62:63] op_sel_hi:[1,0]
	v_pk_mul_f32 v[170:171], v[2:3], v[170:171]
	v_pk_mul_f32 v[168:169], v[4:5], v[168:169]
	s_waitcnt vmcnt(14)
	v_pk_add_f32 v[116:117], v[116:117], 1.0 op_sel_hi:[1,0]
	v_pk_add_f32 v[114:115], v[114:115], 1.0 op_sel_hi:[1,0]
	s_waitcnt vmcnt(13)
	v_pk_add_f32 v[120:121], v[120:121], 1.0 op_sel_hi:[1,0]
	v_pk_add_f32 v[118:119], v[118:119], 1.0 op_sel_hi:[1,0]
	s_waitcnt vmcnt(12)
	v_pk_add_f32 v[124:125], v[124:125], 1.0 op_sel_hi:[1,0]
	v_pk_add_f32 v[122:123], v[122:123], 1.0 op_sel_hi:[1,0]
	v_pk_mul_f32 v[174:175], v[6:7], v[174:175]
	v_pk_mul_f32 v[172:173], v[8:9], v[172:173]
	v_pk_mul_f32 v[178:179], v[10:11], v[178:179]
	v_pk_mul_f32 v[176:177], v[12:13], v[176:177]
	v_pk_mul_f32 v[182:183], v[14:15], v[182:183]
	v_pk_mul_f32 v[180:181], v[16:17], v[180:181]
	v_pk_fma_f32 v[168:169], v[168:169], v[112:113], v[96:97]
	v_pk_fma_f32 v[170:171], v[170:171], v[110:111], v[94:95]
	v_lshl_add_u64 v[38:39], v[38:39], 0, s[22:23]
	v_pk_fma_f32 v[172:173], v[172:173], v[116:117], v[100:101]
	v_pk_fma_f32 v[174:175], v[174:175], v[114:115], v[98:99]
	v_pk_fma_f32 v[176:177], v[176:177], v[120:121], v[104:105]
	v_pk_fma_f32 v[178:179], v[178:179], v[118:119], v[102:103]
	v_pk_fma_f32 v[180:181], v[180:181], v[124:125], v[108:109]
	v_pk_fma_f32 v[182:183], v[182:183], v[122:123], v[106:107]
	v_cvt_pk_bf16_f32 v170, v170, v171
	v_cvt_pk_bf16_f32 v171, v168, v169
	v_cvt_pk_bf16_f32 v168, v174, v175
	v_cvt_pk_bf16_f32 v169, v172, v173
	v_cvt_pk_bf16_f32 v172, v178, v179
	v_cvt_pk_bf16_f32 v173, v176, v177
	v_cvt_pk_bf16_f32 v174, v182, v183
	v_cvt_pk_bf16_f32 v175, v180, v181
	global_store_dwordx2 v[126:127], v[170:171], off sc1
	global_store_dwordx2 v[126:127], v[168:169], off offset:512 sc1
	global_store_dwordx2 v[126:127], v[172:173], off offset:1024 sc1
	global_store_dwordx2 v[126:127], v[174:175], off offset:1536 sc1
	s_cbranch_scc1 .Lnpf1_done
	s_branch .Lnpf1_a
.Lnpf1_done:
.LBB0_197:
	s_mov_b64 s[8:9], 0
	v_readlane_b32 s27, v255, 31

.LBB0_243:
	s_andn2_b64 vcc, exec, s[22:23]
	s_cbranch_vccnz .LBB0_277
	s_add_i32 s22, s6, 0xfffff400
	s_add_i32 s23, s6, 0xfffff3e0
	s_cmp_lt_u32 s22, 32
	s_cselect_b32 s45, s22, s23
	s_cmp_gt_u32 s22, 31
	s_cselect_b32 s29, 64, 0
	s_lshl_b32 s28, s45, 5
	v_or_b32_e32 v39, s28, v2
	s_movk_i32 s22, 0x3ff
	v_cmp_lt_i32_e32 vcc, s22, v39
	s_load_dwordx2 s[46:47], s[0:1], 0x78
	s_lshl_b32 s45, s45, 6
	v_bitop3_b32 v39, s28, 63, v2 bitop3:0xc8
	v_or3_b32 v46, v39, s45, 64
	v_ashrrev_i32_e32 v47, 31, v46
	s_waitcnt lgkmcnt(0)
	v_lshl_add_u64 v[46:47], v[46:47], 2, s[46:47]
	v_mov_b32_e32 v108, 0
	v_mov_b32_e32 v109, 0
	v_mov_b32_e32 v110, 0
	v_mov_b32_e32 v111, 0
	v_mov_b32_e32 v112, 0
	v_mov_b32_e32 v113, 0
	v_mov_b32_e32 v114, 0
	v_mov_b32_e32 v115, 0
	v_mov_b32_e32 v116, 0
	v_mov_b32_e32 v117, 0
	v_mov_b32_e32 v118, 0
	v_mov_b32_e32 v119, 0
	v_mov_b32_e32 v120, 0
	v_mov_b32_e32 v121, 0
	v_mov_b32_e32 v122, 0
	v_mov_b32_e32 v123, 0
	v_mov_b32_e32 v124, 0
	v_mov_b32_e32 v125, 0
	v_mov_b32_e32 v126, 0
	v_mov_b32_e32 v127, 0
	v_mov_b32_e32 v128, 0
	v_mov_b32_e32 v129, 0
	v_mov_b32_e32 v130, 0
	v_mov_b32_e32 v131, 0
	v_mov_b32_e32 v132, 0
	v_mov_b32_e32 v133, 0
	v_mov_b32_e32 v134, 0
	v_mov_b32_e32 v135, 0
	v_mov_b32_e32 v136, 0
	v_mov_b32_e32 v137, 0
	v_mov_b32_e32 v41, 0
	v_mov_b32_e32 v43, 0
	s_mov_b64 s[22:23], exec
	s_andn2_b64 exec, exec, vcc
	v_or_b32_e32 v45, s29, v1
	v_lshlrev_b32_e32 v102, 13, v45
	v_mov_b32_e32 v103, v0
	v_lshl_add_u64 v[102:103], v[46:47], 0, v[102:103]
	global_load_dword v108, v[102:103], off nt
	v_or_b32_e32 v45, s29, v55
	v_lshlrev_b32_e32 v104, 13, v45
	v_mov_b32_e32 v105, v0
	v_lshl_add_u64 v[104:105], v[46:47], 0, v[104:105]
	global_load_dword v109, v[104:105], off nt
	v_or_b32_e32 v45, s29, v56
	v_lshlrev_b32_e32 v106, 13, v45
	v_mov_b32_e32 v107, v0
	v_lshl_add_u64 v[106:107], v[46:47], 0, v[106:107]
	global_load_dword v110, v[106:107], off nt
	v_or_b32_e32 v45, s29, v58
	v_lshlrev_b32_e32 v102, 13, v45
	v_mov_b32_e32 v103, v0
	v_lshl_add_u64 v[102:103], v[46:47], 0, v[102:103]
	global_load_dword v111, v[102:103], off nt
	v_or_b32_e32 v45, s29, v59
	v_lshlrev_b32_e32 v104, 13, v45
	v_mov_b32_e32 v105, v0
	v_lshl_add_u64 v[104:105], v[46:47], 0, v[104:105]
	global_load_dword v112, v[104:105], off nt
	v_or_b32_e32 v45, s29, v61
	v_lshlrev_b32_e32 v106, 13, v45
	v_mov_b32_e32 v107, v0
	v_lshl_add_u64 v[106:107], v[46:47], 0, v[106:107]
	global_load_dword v113, v[106:107], off nt
	v_or_b32_e32 v45, s29, v62
	v_lshlrev_b32_e32 v102, 13, v45
	v_mov_b32_e32 v103, v0
	v_lshl_add_u64 v[102:103], v[46:47], 0, v[102:103]
	global_load_dword v114, v[102:103], off nt
	v_or_b32_e32 v45, s29, v64
	v_lshlrev_b32_e32 v104, 13, v45
	v_mov_b32_e32 v105, v0
	v_lshl_add_u64 v[104:105], v[46:47], 0, v[104:105]
	global_load_dword v115, v[104:105], off nt
	v_or_b32_e32 v45, s29, v65
	v_lshlrev_b32_e32 v106, 13, v45
	v_mov_b32_e32 v107, v0
	v_lshl_add_u64 v[106:107], v[46:47], 0, v[106:107]
	global_load_dword v116, v[106:107], off nt
	v_or_b32_e32 v45, s29, v67
	v_lshlrev_b32_e32 v102, 13, v45
	v_mov_b32_e32 v103, v0
	v_lshl_add_u64 v[102:103], v[46:47], 0, v[102:103]
	global_load_dword v117, v[102:103], off nt
	v_or_b32_e32 v45, s29, v68
	v_lshlrev_b32_e32 v104, 13, v45
	v_mov_b32_e32 v105, v0
	v_lshl_add_u64 v[104:105], v[46:47], 0, v[104:105]
	global_load_dword v118, v[104:105], off nt
	v_or_b32_e32 v45, s29, v70
	v_lshlrev_b32_e32 v106, 13, v45
	v_mov_b32_e32 v107, v0
	v_lshl_add_u64 v[106:107], v[46:47], 0, v[106:107]
	global_load_dword v119, v[106:107], off nt
	v_or_b32_e32 v45, s29, v71
	v_lshlrev_b32_e32 v102, 13, v45
	v_mov_b32_e32 v103, v0
	v_lshl_add_u64 v[102:103], v[46:47], 0, v[102:103]
	global_load_dword v120, v[102:103], off nt
	v_or_b32_e32 v45, s29, v73
	v_lshlrev_b32_e32 v104, 13, v45
	v_mov_b32_e32 v105, v0
	v_lshl_add_u64 v[104:105], v[46:47], 0, v[104:105]
	global_load_dword v121, v[104:105], off nt
	v_or_b32_e32 v45, s29, v74
	v_lshlrev_b32_e32 v106, 13, v45
	v_mov_b32_e32 v107, v0
	v_lshl_add_u64 v[106:107], v[46:47], 0, v[106:107]
	global_load_dword v122, v[106:107], off nt
	v_or_b32_e32 v45, s29, v76
	v_lshlrev_b32_e32 v102, 13, v45
	v_mov_b32_e32 v103, v0
	v_lshl_add_u64 v[102:103], v[46:47], 0, v[102:103]
	global_load_dword v123, v[102:103], off nt
	v_or_b32_e32 v45, s29, v77
	v_lshlrev_b32_e32 v104, 13, v45
	v_mov_b32_e32 v105, v0
	v_lshl_add_u64 v[104:105], v[46:47], 0, v[104:105]
	global_load_dword v124, v[104:105], off nt
	v_or_b32_e32 v45, s29, v79
	v_lshlrev_b32_e32 v106, 13, v45
	v_mov_b32_e32 v107, v0
	v_lshl_add_u64 v[106:107], v[46:47], 0, v[106:107]
	global_load_dword v125, v[106:107], off nt
	v_or_b32_e32 v45, s29, v80
	v_lshlrev_b32_e32 v102, 13, v45
	v_mov_b32_e32 v103, v0
	v_lshl_add_u64 v[102:103], v[46:47], 0, v[102:103]
	global_load_dword v126, v[102:103], off nt
	v_or_b32_e32 v45, s29, v82
	v_lshlrev_b32_e32 v104, 13, v45
	v_mov_b32_e32 v105, v0
	v_lshl_add_u64 v[104:105], v[46:47], 0, v[104:105]
	global_load_dword v127, v[104:105], off nt
	v_or_b32_e32 v45, s29, v83
	v_lshlrev_b32_e32 v106, 13, v45
	v_mov_b32_e32 v107, v0
	v_lshl_add_u64 v[106:107], v[46:47], 0, v[106:107]
	global_load_dword v128, v[106:107], off nt
	v_or_b32_e32 v45, s29, v85
	v_lshlrev_b32_e32 v102, 13, v45
	v_mov_b32_e32 v103, v0
	v_lshl_add_u64 v[102:103], v[46:47], 0, v[102:103]
	global_load_dword v129, v[102:103], off nt
	v_or_b32_e32 v45, s29, v86
	v_lshlrev_b32_e32 v104, 13, v45
	v_mov_b32_e32 v105, v0
	v_lshl_add_u64 v[104:105], v[46:47], 0, v[104:105]
	global_load_dword v130, v[104:105], off nt
	v_or_b32_e32 v45, s29, v88
	v_lshlrev_b32_e32 v106, 13, v45
	v_mov_b32_e32 v107, v0
	v_lshl_add_u64 v[106:107], v[46:47], 0, v[106:107]
	global_load_dword v131, v[106:107], off nt
	v_or_b32_e32 v45, s29, v89
	v_lshlrev_b32_e32 v102, 13, v45
	v_mov_b32_e32 v103, v0
	v_lshl_add_u64 v[102:103], v[46:47], 0, v[102:103]
	global_load_dword v132, v[102:103], off nt
	v_or_b32_e32 v45, s29, v91
	v_lshlrev_b32_e32 v104, 13, v45
	v_mov_b32_e32 v105, v0
	v_lshl_add_u64 v[104:105], v[46:47], 0, v[104:105]
	global_load_dword v133, v[104:105], off nt
	v_or_b32_e32 v45, s29, v92
	v_lshlrev_b32_e32 v106, 13, v45
	v_mov_b32_e32 v107, v0
	v_lshl_add_u64 v[106:107], v[46:47], 0, v[106:107]
	global_load_dword v134, v[106:107], off nt
	v_or_b32_e32 v45, s29, v93
	v_lshlrev_b32_e32 v102, 13, v45
	v_mov_b32_e32 v103, v0
	v_lshl_add_u64 v[102:103], v[46:47], 0, v[102:103]
	global_load_dword v135, v[102:103], off nt
	v_or_b32_e32 v45, s29, v94
	v_lshlrev_b32_e32 v104, 13, v45
	v_mov_b32_e32 v105, v0
	v_lshl_add_u64 v[104:105], v[46:47], 0, v[104:105]
	global_load_dword v136, v[104:105], off nt
	v_or_b32_e32 v45, s29, v95
	v_lshlrev_b32_e32 v106, 13, v45
	v_mov_b32_e32 v107, v0
	v_lshl_add_u64 v[106:107], v[46:47], 0, v[106:107]
	global_load_dword v137, v[106:107], off nt
	v_or_b32_e32 v45, s29, v96
	v_lshlrev_b32_e32 v102, 13, v45
	v_mov_b32_e32 v103, v0
	v_lshl_add_u64 v[102:103], v[46:47], 0, v[102:103]
	global_load_dword v41, v[102:103], off nt
	v_or_b32_e32 v45, s29, v97
	v_lshlrev_b32_e32 v104, 13, v45
	v_mov_b32_e32 v105, v0
	v_lshl_add_u64 v[104:105], v[46:47], 0, v[104:105]
	global_load_dword v43, v[104:105], off nt
	s_mov_b64 exec, s[22:23]
	v_add_u32_e32 v39, v53, v54
	s_waitcnt vmcnt(30)
	ds_write2_b32 v39, v108, v109 offset1:66
	v_add_u32_e32 v39, v53, v57
	s_waitcnt vmcnt(28)
	ds_write2_b32 v39, v110, v111 offset1:66
	v_add_u32_e32 v39, v53, v60
	s_waitcnt vmcnt(26)
	ds_write2_b32 v39, v112, v113 offset1:66
	v_add_u32_e32 v39, v53, v63
	s_waitcnt vmcnt(24)
	ds_write2_b32 v39, v114, v115 offset1:66
	v_add_u32_e32 v39, v53, v66
	s_waitcnt vmcnt(22)
	ds_write2_b32 v39, v116, v117 offset1:66
	v_add_u32_e32 v39, v53, v69
	s_waitcnt vmcnt(20)
	ds_write2_b32 v39, v118, v119 offset1:66
	v_add_u32_e32 v39, v53, v72
	s_waitcnt vmcnt(18)
	ds_write2_b32 v39, v120, v121 offset1:66
	v_add_u32_e32 v39, v53, v75
	s_waitcnt vmcnt(16)
	ds_write2_b32 v39, v122, v123 offset1:66
	v_add_u32_e32 v39, v53, v78
	s_waitcnt vmcnt(14)
	ds_write2_b32 v39, v124, v125 offset1:66
	v_add_u32_e32 v39, v53, v81
	s_waitcnt vmcnt(12)
	ds_write2_b32 v39, v126, v127 offset1:66
	v_add_u32_e32 v39, v53, v84
	s_waitcnt vmcnt(10)
	ds_write2_b32 v39, v128, v129 offset1:66
	v_add_u32_e32 v39, v53, v87
	s_waitcnt vmcnt(8)
	ds_write2_b32 v39, v130, v131 offset1:66
	v_add_u32_e32 v39, v53, v90
	s_waitcnt vmcnt(6)
	ds_write2_b32 v39, v132, v133 offset1:66
	s_waitcnt vmcnt(4)
	ds_write2_b32 v39, v134, v135 offset0:132 offset1:198
	v_add_u32_e32 v39, 0x400, v39
	s_waitcnt vmcnt(2)
	ds_write2_b32 v39, v136, v137 offset0:8 offset1:74
	s_waitcnt vmcnt(0)
	ds_write2_b32 v39, v41, v43 offset0:140 offset1:206
	s_waitcnt lgkmcnt(0)
	ds_read2_b32 v[46:47], v48 offset0:33 offset1:41
	ds_read2_b32 v[106:107], v48 offset1:8
	ds_read2_b32 v[108:109], v48 offset0:66 offset1:74
	ds_read2_b32 v[110:111], v48 offset0:99 offset1:107
	ds_read2_b32 v[112:113], v48 offset0:132 offset1:140
	ds_read2_b32 v[114:115], v48 offset0:165 offset1:173
	ds_read2_b32 v[116:117], v48 offset0:198 offset1:206
	ds_read2_b32 v[118:119], v48 offset0:231 offset1:239
	v_or_b32_e32 v122, s28, v3
	s_lshl_b32 s58, s29, 1
	v_ashrrev_i32_e32 v123, 31, v122
	v_lshl_add_u64 v[120:121], v[14:15], 0, s[58:59]
	v_lshlrev_b64 v[122:123], 8, v[122:123]
	s_waitcnt lgkmcnt(6)
	v_cvt_pk_bf16_f32 v102, v106, v46
	s_waitcnt lgkmcnt(4)
	v_cvt_pk_bf16_f32 v103, v108, v110
	s_waitcnt lgkmcnt(2)
	v_cvt_pk_bf16_f32 v104, v112, v114
	s_waitcnt lgkmcnt(0)
	v_cvt_pk_bf16_f32 v105, v116, v118
	v_lshl_add_u64 v[122:123], v[120:121], 0, v[122:123]
	v_or_b32_e32 v46, s28, v50
	global_store_dwordx4 v[122:123], v[102:105], off
	s_nop 1
	v_cvt_pk_bf16_f32 v102, v107, v47
	v_ashrrev_i32_e32 v47, 31, v46
	v_cvt_pk_bf16_f32 v103, v109, v111
	v_cvt_pk_bf16_f32 v104, v113, v115
	v_cvt_pk_bf16_f32 v105, v117, v119
	v_lshlrev_b64 v[46:47], 8, v[46:47]
	ds_read2_b32 v[106:107], v48 offset0:49 offset1:57
	ds_read2_b32 v[108:109], v48 offset0:16 offset1:24
	ds_read2_b32 v[110:111], v48 offset0:82 offset1:90
	ds_read2_b32 v[112:113], v48 offset0:115 offset1:123
	ds_read2_b32 v[114:115], v48 offset0:148 offset1:156
	ds_read2_b32 v[116:117], v48 offset0:181 offset1:189
	ds_read2_b32 v[118:119], v48 offset0:214 offset1:222
	ds_read2_b32 v[122:123], v48 offset0:247 offset1:255
	v_lshl_add_u64 v[46:47], v[120:121], 0, v[46:47]
	global_store_dwordx4 v[46:47], v[102:105], off
	v_or_b32_e32 v46, s28, v51
	v_ashrrev_i32_e32 v47, 31, v46
	v_lshlrev_b64 v[46:47], 8, v[46:47]
	s_waitcnt lgkmcnt(6)
	v_cvt_pk_bf16_f32 v102, v108, v106
	s_waitcnt lgkmcnt(4)
	v_cvt_pk_bf16_f32 v103, v110, v112
	s_waitcnt lgkmcnt(2)
	v_cvt_pk_bf16_f32 v104, v114, v116
	s_waitcnt lgkmcnt(0)
	v_cvt_pk_bf16_f32 v105, v118, v122
	v_lshl_add_u64 v[46:47], v[120:121], 0, v[46:47]
	global_store_dwordx4 v[46:47], v[102:105], off
	v_or_b32_e32 v46, s28, v52
	v_ashrrev_i32_e32 v47, 31, v46
	v_lshlrev_b64 v[46:47], 8, v[46:47]
	v_cvt_pk_bf16_f32 v102, v109, v107
	v_cvt_pk_bf16_f32 v103, v111, v113
	v_cvt_pk_bf16_f32 v104, v115, v117
	v_cvt_pk_bf16_f32 v105, v119, v123
	v_lshl_add_u64 v[46:47], v[120:121], 0, v[46:47]
	global_store_dwordx4 v[46:47], v[102:105], off
	s_waitcnt lgkmcnt(0)

.LBB0_278:
	s_andn2_b64 vcc, exec, s[22:23]
	s_cbranch_vccnz .LBB0_312
	s_add_i32 s22, s6, 0xfffff440
	s_add_i32 s23, s6, 0xfffff420
	s_cmp_lt_u32 s22, 32
	s_cselect_b32 s45, s22, s23
	s_cmp_gt_u32 s22, 31
	s_cselect_b32 s29, 64, 0
	s_lshl_b32 s28, s45, 5
	v_or_b32_e32 v39, s28, v2
	s_movk_i32 s22, 0x3ff
	v_cmp_lt_i32_e32 vcc, s22, v39
	s_load_dwordx2 s[46:47], s[0:1], 0x78
	s_lshl_b32 s45, s45, 6
	s_and_b32 s45, s45, 0xffffff80
	v_and_or_b32 v46, v39, 63, s45
	v_ashrrev_i32_e32 v47, 31, v46
	s_waitcnt lgkmcnt(0)
	v_lshl_add_u64 v[46:47], v[46:47], 2, s[46:47]
	v_mov_b32_e32 v108, 0
	v_mov_b32_e32 v109, 0
	v_mov_b32_e32 v110, 0
	v_mov_b32_e32 v111, 0
	v_mov_b32_e32 v112, 0
	v_mov_b32_e32 v113, 0
	v_mov_b32_e32 v114, 0
	v_mov_b32_e32 v115, 0
	v_mov_b32_e32 v116, 0
	v_mov_b32_e32 v117, 0
	v_mov_b32_e32 v118, 0
	v_mov_b32_e32 v119, 0
	v_mov_b32_e32 v120, 0
	v_mov_b32_e32 v121, 0
	v_mov_b32_e32 v122, 0
	v_mov_b32_e32 v123, 0
	v_mov_b32_e32 v124, 0
	v_mov_b32_e32 v125, 0
	v_mov_b32_e32 v126, 0
	v_mov_b32_e32 v127, 0
	v_mov_b32_e32 v128, 0
	v_mov_b32_e32 v129, 0
	v_mov_b32_e32 v130, 0
	v_mov_b32_e32 v131, 0
	v_mov_b32_e32 v132, 0
	v_mov_b32_e32 v133, 0
	v_mov_b32_e32 v134, 0
	v_mov_b32_e32 v135, 0
	v_mov_b32_e32 v136, 0
	v_mov_b32_e32 v137, 0
	v_mov_b32_e32 v41, 0
	v_mov_b32_e32 v43, 0
	s_mov_b64 s[22:23], exec
	s_andn2_b64 exec, exec, vcc
	v_or_b32_e32 v45, s29, v1
	v_lshlrev_b32_e32 v102, 13, v45
	v_mov_b32_e32 v103, v0
	v_lshl_add_u64 v[102:103], v[46:47], 0, v[102:103]
	global_load_dword v108, v[102:103], off nt
	v_or_b32_e32 v45, s29, v55
	v_lshlrev_b32_e32 v104, 13, v45
	v_mov_b32_e32 v105, v0
	v_lshl_add_u64 v[104:105], v[46:47], 0, v[104:105]
	global_load_dword v109, v[104:105], off nt
	v_or_b32_e32 v45, s29, v56
	v_lshlrev_b32_e32 v106, 13, v45
	v_mov_b32_e32 v107, v0
	v_lshl_add_u64 v[106:107], v[46:47], 0, v[106:107]
	global_load_dword v110, v[106:107], off nt
	v_or_b32_e32 v45, s29, v58
	v_lshlrev_b32_e32 v102, 13, v45
	v_mov_b32_e32 v103, v0
	v_lshl_add_u64 v[102:103], v[46:47], 0, v[102:103]
	global_load_dword v111, v[102:103], off nt
	v_or_b32_e32 v45, s29, v59
	v_lshlrev_b32_e32 v104, 13, v45
	v_mov_b32_e32 v105, v0
	v_lshl_add_u64 v[104:105], v[46:47], 0, v[104:105]
	global_load_dword v112, v[104:105], off nt
	v_or_b32_e32 v45, s29, v61
	v_lshlrev_b32_e32 v106, 13, v45
	v_mov_b32_e32 v107, v0
	v_lshl_add_u64 v[106:107], v[46:47], 0, v[106:107]
	global_load_dword v113, v[106:107], off nt
	v_or_b32_e32 v45, s29, v62
	v_lshlrev_b32_e32 v102, 13, v45
	v_mov_b32_e32 v103, v0
	v_lshl_add_u64 v[102:103], v[46:47], 0, v[102:103]
	global_load_dword v114, v[102:103], off nt
	v_or_b32_e32 v45, s29, v64
	v_lshlrev_b32_e32 v104, 13, v45
	v_mov_b32_e32 v105, v0
	v_lshl_add_u64 v[104:105], v[46:47], 0, v[104:105]
	global_load_dword v115, v[104:105], off nt
	v_or_b32_e32 v45, s29, v65
	v_lshlrev_b32_e32 v106, 13, v45
	v_mov_b32_e32 v107, v0
	v_lshl_add_u64 v[106:107], v[46:47], 0, v[106:107]
	global_load_dword v116, v[106:107], off nt
	v_or_b32_e32 v45, s29, v67
	v_lshlrev_b32_e32 v102, 13, v45
	v_mov_b32_e32 v103, v0
	v_lshl_add_u64 v[102:103], v[46:47], 0, v[102:103]
	global_load_dword v117, v[102:103], off nt
	v_or_b32_e32 v45, s29, v68
	v_lshlrev_b32_e32 v104, 13, v45
	v_mov_b32_e32 v105, v0
	v_lshl_add_u64 v[104:105], v[46:47], 0, v[104:105]
	global_load_dword v118, v[104:105], off nt
	v_or_b32_e32 v45, s29, v70
	v_lshlrev_b32_e32 v106, 13, v45
	v_mov_b32_e32 v107, v0
	v_lshl_add_u64 v[106:107], v[46:47], 0, v[106:107]
	global_load_dword v119, v[106:107], off nt
	v_or_b32_e32 v45, s29, v71
	v_lshlrev_b32_e32 v102, 13, v45
	v_mov_b32_e32 v103, v0
	v_lshl_add_u64 v[102:103], v[46:47], 0, v[102:103]
	global_load_dword v120, v[102:103], off nt
	v_or_b32_e32 v45, s29, v73
	v_lshlrev_b32_e32 v104, 13, v45
	v_mov_b32_e32 v105, v0
	v_lshl_add_u64 v[104:105], v[46:47], 0, v[104:105]
	global_load_dword v121, v[104:105], off nt
	v_or_b32_e32 v45, s29, v74
	v_lshlrev_b32_e32 v106, 13, v45
	v_mov_b32_e32 v107, v0
	v_lshl_add_u64 v[106:107], v[46:47], 0, v[106:107]
	global_load_dword v122, v[106:107], off nt
	v_or_b32_e32 v45, s29, v76
	v_lshlrev_b32_e32 v102, 13, v45
	v_mov_b32_e32 v103, v0
	v_lshl_add_u64 v[102:103], v[46:47], 0, v[102:103]
	global_load_dword v123, v[102:103], off nt
	v_or_b32_e32 v45, s29, v77
	v_lshlrev_b32_e32 v104, 13, v45
	v_mov_b32_e32 v105, v0
	v_lshl_add_u64 v[104:105], v[46:47], 0, v[104:105]
	global_load_dword v124, v[104:105], off nt
	v_or_b32_e32 v45, s29, v79
	v_lshlrev_b32_e32 v106, 13, v45
	v_mov_b32_e32 v107, v0
	v_lshl_add_u64 v[106:107], v[46:47], 0, v[106:107]
	global_load_dword v125, v[106:107], off nt
	v_or_b32_e32 v45, s29, v80
	v_lshlrev_b32_e32 v102, 13, v45
	v_mov_b32_e32 v103, v0
	v_lshl_add_u64 v[102:103], v[46:47], 0, v[102:103]
	global_load_dword v126, v[102:103], off nt
	v_or_b32_e32 v45, s29, v82
	v_lshlrev_b32_e32 v104, 13, v45
	v_mov_b32_e32 v105, v0
	v_lshl_add_u64 v[104:105], v[46:47], 0, v[104:105]
	global_load_dword v127, v[104:105], off nt
	v_or_b32_e32 v45, s29, v83
	v_lshlrev_b32_e32 v106, 13, v45
	v_mov_b32_e32 v107, v0
	v_lshl_add_u64 v[106:107], v[46:47], 0, v[106:107]
	global_load_dword v128, v[106:107], off nt
	v_or_b32_e32 v45, s29, v85
	v_lshlrev_b32_e32 v102, 13, v45
	v_mov_b32_e32 v103, v0
	v_lshl_add_u64 v[102:103], v[46:47], 0, v[102:103]
	global_load_dword v129, v[102:103], off nt
	v_or_b32_e32 v45, s29, v86
	v_lshlrev_b32_e32 v104, 13, v45
	v_mov_b32_e32 v105, v0
	v_lshl_add_u64 v[104:105], v[46:47], 0, v[104:105]
	global_load_dword v130, v[104:105], off nt
	v_or_b32_e32 v45, s29, v88
	v_lshlrev_b32_e32 v106, 13, v45
	v_mov_b32_e32 v107, v0
	v_lshl_add_u64 v[106:107], v[46:47], 0, v[106:107]
	global_load_dword v131, v[106:107], off nt
	v_or_b32_e32 v45, s29, v89
	v_lshlrev_b32_e32 v102, 13, v45
	v_mov_b32_e32 v103, v0
	v_lshl_add_u64 v[102:103], v[46:47], 0, v[102:103]
	global_load_dword v132, v[102:103], off nt
	v_or_b32_e32 v45, s29, v91
	v_lshlrev_b32_e32 v104, 13, v45
	v_mov_b32_e32 v105, v0
	v_lshl_add_u64 v[104:105], v[46:47], 0, v[104:105]
	global_load_dword v133, v[104:105], off nt
	v_or_b32_e32 v45, s29, v92
	v_lshlrev_b32_e32 v106, 13, v45
	v_mov_b32_e32 v107, v0
	v_lshl_add_u64 v[106:107], v[46:47], 0, v[106:107]
	global_load_dword v134, v[106:107], off nt
	v_or_b32_e32 v45, s29, v93
	v_lshlrev_b32_e32 v102, 13, v45
	v_mov_b32_e32 v103, v0
	v_lshl_add_u64 v[102:103], v[46:47], 0, v[102:103]
	global_load_dword v135, v[102:103], off nt
	v_or_b32_e32 v45, s29, v94
	v_lshlrev_b32_e32 v104, 13, v45
	v_mov_b32_e32 v105, v0
	v_lshl_add_u64 v[104:105], v[46:47], 0, v[104:105]
	global_load_dword v136, v[104:105], off nt
	v_or_b32_e32 v45, s29, v95
	v_lshlrev_b32_e32 v106, 13, v45
	v_mov_b32_e32 v107, v0
	v_lshl_add_u64 v[106:107], v[46:47], 0, v[106:107]
	global_load_dword v137, v[106:107], off nt
	v_or_b32_e32 v45, s29, v96
	v_lshlrev_b32_e32 v102, 13, v45
	v_mov_b32_e32 v103, v0
	v_lshl_add_u64 v[102:103], v[46:47], 0, v[102:103]
	global_load_dword v41, v[102:103], off nt
	v_or_b32_e32 v45, s29, v97
	v_lshlrev_b32_e32 v104, 13, v45
	v_mov_b32_e32 v105, v0
	v_lshl_add_u64 v[104:105], v[46:47], 0, v[104:105]
	global_load_dword v43, v[104:105], off nt
	s_mov_b64 exec, s[22:23]
	v_add_u32_e32 v39, v53, v54
	s_waitcnt vmcnt(30)
	ds_write2_b32 v39, v108, v109 offset1:66
	v_add_u32_e32 v39, v53, v57
	s_waitcnt vmcnt(28)
	ds_write2_b32 v39, v110, v111 offset1:66
	v_add_u32_e32 v39, v53, v60
	s_waitcnt vmcnt(26)
	ds_write2_b32 v39, v112, v113 offset1:66
	v_add_u32_e32 v39, v53, v63
	s_waitcnt vmcnt(24)
	ds_write2_b32 v39, v114, v115 offset1:66
	v_add_u32_e32 v39, v53, v66
	s_waitcnt vmcnt(22)
	ds_write2_b32 v39, v116, v117 offset1:66
	v_add_u32_e32 v39, v53, v69
	s_waitcnt vmcnt(20)
	ds_write2_b32 v39, v118, v119 offset1:66
	v_add_u32_e32 v39, v53, v72
	s_waitcnt vmcnt(18)
	ds_write2_b32 v39, v120, v121 offset1:66
	v_add_u32_e32 v39, v53, v75
	s_waitcnt vmcnt(16)
	ds_write2_b32 v39, v122, v123 offset1:66
	v_add_u32_e32 v39, v53, v78
	s_waitcnt vmcnt(14)
	ds_write2_b32 v39, v124, v125 offset1:66
	v_add_u32_e32 v39, v53, v81
	s_waitcnt vmcnt(12)
	ds_write2_b32 v39, v126, v127 offset1:66
	v_add_u32_e32 v39, v53, v84
	s_waitcnt vmcnt(10)
	ds_write2_b32 v39, v128, v129 offset1:66
	v_add_u32_e32 v39, v53, v87
	s_waitcnt vmcnt(8)
	ds_write2_b32 v39, v130, v131 offset1:66
	v_add_u32_e32 v39, v53, v90
	s_waitcnt vmcnt(6)
	ds_write2_b32 v39, v132, v133 offset1:66
	s_waitcnt vmcnt(4)
	ds_write2_b32 v39, v134, v135 offset0:132 offset1:198
	v_add_u32_e32 v39, 0x400, v39
	s_waitcnt vmcnt(2)
	ds_write2_b32 v39, v136, v137 offset0:8 offset1:74
	s_waitcnt vmcnt(0)
	ds_write2_b32 v39, v41, v43 offset0:140 offset1:206
	s_waitcnt lgkmcnt(0)
	ds_read2_b32 v[46:47], v48 offset0:33 offset1:41
	ds_read2_b32 v[106:107], v48 offset1:8
	ds_read2_b32 v[108:109], v48 offset0:66 offset1:74
	ds_read2_b32 v[110:111], v48 offset0:99 offset1:107
	ds_read2_b32 v[112:113], v48 offset0:132 offset1:140
	ds_read2_b32 v[114:115], v48 offset0:165 offset1:173
	ds_read2_b32 v[116:117], v48 offset0:198 offset1:206
	ds_read2_b32 v[118:119], v48 offset0:231 offset1:239
	v_or_b32_e32 v122, s28, v3
	s_lshl_b32 s58, s29, 1
	v_ashrrev_i32_e32 v123, 31, v122
	v_lshl_add_u64 v[120:121], v[16:17], 0, s[58:59]
	v_lshlrev_b64 v[122:123], 8, v[122:123]
	s_waitcnt lgkmcnt(6)
	v_cvt_pk_bf16_f32 v102, v106, v46
	s_waitcnt lgkmcnt(4)
	v_cvt_pk_bf16_f32 v103, v108, v110
	s_waitcnt lgkmcnt(2)
	v_cvt_pk_bf16_f32 v104, v112, v114
	s_waitcnt lgkmcnt(0)
	v_cvt_pk_bf16_f32 v105, v116, v118
	v_lshl_add_u64 v[122:123], v[120:121], 0, v[122:123]
	v_or_b32_e32 v46, s28, v50
	global_store_dwordx4 v[122:123], v[102:105], off
	s_nop 1
	v_cvt_pk_bf16_f32 v102, v107, v47
	v_ashrrev_i32_e32 v47, 31, v46
	v_cvt_pk_bf16_f32 v103, v109, v111
	v_cvt_pk_bf16_f32 v104, v113, v115
	v_cvt_pk_bf16_f32 v105, v117, v119
	v_lshlrev_b64 v[46:47], 8, v[46:47]
	ds_read2_b32 v[106:107], v48 offset0:49 offset1:57
	ds_read2_b32 v[108:109], v48 offset0:16 offset1:24
	ds_read2_b32 v[110:111], v48 offset0:82 offset1:90
	ds_read2_b32 v[112:113], v48 offset0:115 offset1:123
	ds_read2_b32 v[114:115], v48 offset0:148 offset1:156
	ds_read2_b32 v[116:117], v48 offset0:181 offset1:189
	ds_read2_b32 v[118:119], v48 offset0:214 offset1:222
	ds_read2_b32 v[122:123], v48 offset0:247 offset1:255
	v_lshl_add_u64 v[46:47], v[120:121], 0, v[46:47]
	global_store_dwordx4 v[46:47], v[102:105], off
	v_or_b32_e32 v46, s28, v51
	v_ashrrev_i32_e32 v47, 31, v46
	v_lshlrev_b64 v[46:47], 8, v[46:47]
	s_waitcnt lgkmcnt(6)
	v_cvt_pk_bf16_f32 v102, v108, v106
	s_waitcnt lgkmcnt(4)
	v_cvt_pk_bf16_f32 v103, v110, v112
	s_waitcnt lgkmcnt(2)
	v_cvt_pk_bf16_f32 v104, v114, v116
	s_waitcnt lgkmcnt(0)
	v_cvt_pk_bf16_f32 v105, v118, v122
	v_lshl_add_u64 v[46:47], v[120:121], 0, v[46:47]
	global_store_dwordx4 v[46:47], v[102:105], off
	v_or_b32_e32 v46, s28, v52
	v_ashrrev_i32_e32 v47, 31, v46
	v_lshlrev_b64 v[46:47], 8, v[46:47]
	v_cvt_pk_bf16_f32 v102, v109, v107
	v_cvt_pk_bf16_f32 v103, v111, v113
	v_cvt_pk_bf16_f32 v104, v115, v117
	v_cvt_pk_bf16_f32 v105, v119, v123
	v_lshl_add_u64 v[46:47], v[120:121], 0, v[46:47]
	global_store_dwordx4 v[46:47], v[102:105], off
	s_waitcnt lgkmcnt(0)

.LBB0_372:
	s_andn2_b64 vcc, exec, s[22:23]
	s_cbranch_vccnz .LBB0_213
	s_ashr_i32 s22, s6, 31
	s_lshr_b32 s22, s22, 28
	s_add_i32 s22, s6, s22
	s_ashr_i32 s46, s22, 4
	s_lshl_b32 s45, s46, 9
	s_sub_i32 s47, s24, s45
	v_add_u32_e32 v41, s47, v2
	s_movk_i32 s22, 0x1ff
	v_cmp_lt_i32_e32 vcc, s22, v41
	v_add_u32_e32 v39, v53, v54
	s_load_dwordx2 s[48:49], s[0:1], 0x30
	v_and_b32_e32 v41, 51, v41
	s_andn2_b32 s47, s47, 63
	v_or3_b32 v46, v49, s47, v41
	v_ashrrev_i32_e32 v47, 31, v46
	s_lshl_b32 s22, s46, 6
	s_waitcnt lgkmcnt(0)
	v_lshl_add_u64 v[46:47], v[46:47], 2, s[48:49]
	s_movk_i32 s23, 0x56c0
	v_mov_b32_e32 v108, 0
	v_mov_b32_e32 v109, 0
	v_mov_b32_e32 v110, 0
	v_mov_b32_e32 v111, 0
	v_mov_b32_e32 v112, 0
	v_mov_b32_e32 v113, 0
	v_mov_b32_e32 v114, 0
	v_mov_b32_e32 v115, 0
	v_mov_b32_e32 v116, 0
	v_mov_b32_e32 v117, 0
	v_mov_b32_e32 v118, 0
	v_mov_b32_e32 v119, 0
	v_mov_b32_e32 v120, 0
	v_mov_b32_e32 v121, 0
	v_mov_b32_e32 v122, 0
	v_mov_b32_e32 v123, 0
	v_mov_b32_e32 v124, 0
	v_mov_b32_e32 v125, 0
	v_mov_b32_e32 v126, 0
	v_mov_b32_e32 v127, 0
	v_mov_b32_e32 v128, 0
	v_mov_b32_e32 v129, 0
	v_mov_b32_e32 v130, 0
	v_mov_b32_e32 v131, 0
	v_mov_b32_e32 v132, 0
	v_mov_b32_e32 v133, 0
	v_mov_b32_e32 v134, 0
	v_mov_b32_e32 v135, 0
	v_mov_b32_e32 v136, 0
	v_mov_b32_e32 v137, 0
	v_mov_b32_e32 v41, 0
	v_mov_b32_e32 v43, 0
	s_mov_b64 s[28:29], exec
	s_andn2_b64 exec, exec, vcc
	v_or_b32_e32 v45, s22, v1
	v_mad_i64_i32 v[102:103], s[46:47], v45, s23, v[46:47]
	global_load_dword v108, v[102:103], off nt
	v_or_b32_e32 v45, s22, v55
	v_mad_i64_i32 v[104:105], s[46:47], v45, s23, v[46:47]
	global_load_dword v109, v[104:105], off nt
	v_or_b32_e32 v45, s22, v56
	v_mad_i64_i32 v[106:107], s[46:47], v45, s23, v[46:47]
	global_load_dword v110, v[106:107], off nt
	v_or_b32_e32 v45, s22, v58
	v_mad_i64_i32 v[102:103], s[46:47], v45, s23, v[46:47]
	global_load_dword v111, v[102:103], off nt
	v_or_b32_e32 v45, s22, v59
	v_mad_i64_i32 v[104:105], s[46:47], v45, s23, v[46:47]
	global_load_dword v112, v[104:105], off nt
	v_or_b32_e32 v45, s22, v61
	v_mad_i64_i32 v[106:107], s[46:47], v45, s23, v[46:47]
	global_load_dword v113, v[106:107], off nt
	v_or_b32_e32 v45, s22, v62
	v_mad_i64_i32 v[102:103], s[46:47], v45, s23, v[46:47]
	global_load_dword v114, v[102:103], off nt
	v_or_b32_e32 v45, s22, v64
	v_mad_i64_i32 v[104:105], s[46:47], v45, s23, v[46:47]
	global_load_dword v115, v[104:105], off nt
	v_or_b32_e32 v45, s22, v65
	v_mad_i64_i32 v[106:107], s[46:47], v45, s23, v[46:47]
	global_load_dword v116, v[106:107], off nt
	v_or_b32_e32 v45, s22, v67
	v_mad_i64_i32 v[102:103], s[46:47], v45, s23, v[46:47]
	global_load_dword v117, v[102:103], off nt
	v_or_b32_e32 v45, s22, v68
	v_mad_i64_i32 v[104:105], s[46:47], v45, s23, v[46:47]
	global_load_dword v118, v[104:105], off nt
	v_or_b32_e32 v45, s22, v70
	v_mad_i64_i32 v[106:107], s[46:47], v45, s23, v[46:47]
	global_load_dword v119, v[106:107], off nt
	v_or_b32_e32 v45, s22, v71
	v_mad_i64_i32 v[102:103], s[46:47], v45, s23, v[46:47]
	global_load_dword v120, v[102:103], off nt
	v_or_b32_e32 v45, s22, v73
	v_mad_i64_i32 v[104:105], s[46:47], v45, s23, v[46:47]
	global_load_dword v121, v[104:105], off nt
	v_or_b32_e32 v45, s22, v74
	v_mad_i64_i32 v[106:107], s[46:47], v45, s23, v[46:47]
	global_load_dword v122, v[106:107], off nt
	v_or_b32_e32 v45, s22, v76
	v_mad_i64_i32 v[102:103], s[46:47], v45, s23, v[46:47]
	global_load_dword v123, v[102:103], off nt
	v_or_b32_e32 v45, s22, v77
	v_mad_i64_i32 v[104:105], s[46:47], v45, s23, v[46:47]
	global_load_dword v124, v[104:105], off nt
	v_or_b32_e32 v45, s22, v79
	v_mad_i64_i32 v[106:107], s[46:47], v45, s23, v[46:47]
	global_load_dword v125, v[106:107], off nt
	v_or_b32_e32 v45, s22, v80
	v_mad_i64_i32 v[102:103], s[46:47], v45, s23, v[46:47]
	global_load_dword v126, v[102:103], off nt
	v_or_b32_e32 v45, s22, v82
	v_mad_i64_i32 v[104:105], s[46:47], v45, s23, v[46:47]
	global_load_dword v127, v[104:105], off nt
	v_or_b32_e32 v45, s22, v83
	v_mad_i64_i32 v[106:107], s[46:47], v45, s23, v[46:47]
	global_load_dword v128, v[106:107], off nt
	v_or_b32_e32 v45, s22, v85
	v_mad_i64_i32 v[102:103], s[46:47], v45, s23, v[46:47]
	global_load_dword v129, v[102:103], off nt
	v_or_b32_e32 v45, s22, v86
	v_mad_i64_i32 v[104:105], s[46:47], v45, s23, v[46:47]
	global_load_dword v130, v[104:105], off nt
	v_or_b32_e32 v45, s22, v88
	v_mad_i64_i32 v[106:107], s[46:47], v45, s23, v[46:47]
	global_load_dword v131, v[106:107], off nt
	v_or_b32_e32 v45, s22, v89
	v_mad_i64_i32 v[102:103], s[46:47], v45, s23, v[46:47]
	global_load_dword v132, v[102:103], off nt
	v_or_b32_e32 v45, s22, v91
	v_mad_i64_i32 v[104:105], s[46:47], v45, s23, v[46:47]
	global_load_dword v133, v[104:105], off nt
	v_or_b32_e32 v45, s22, v92
	v_mad_i64_i32 v[106:107], s[46:47], v45, s23, v[46:47]
	global_load_dword v134, v[106:107], off nt
	v_or_b32_e32 v45, s22, v93
	v_mad_i64_i32 v[102:103], s[46:47], v45, s23, v[46:47]
	global_load_dword v135, v[102:103], off nt
	v_or_b32_e32 v45, s22, v94
	v_mad_i64_i32 v[104:105], s[46:47], v45, s23, v[46:47]
	global_load_dword v136, v[104:105], off nt
	v_or_b32_e32 v45, s22, v95
	v_mad_i64_i32 v[106:107], s[46:47], v45, s23, v[46:47]
	global_load_dword v137, v[106:107], off nt
	v_or_b32_e32 v45, s22, v96
	v_mad_i64_i32 v[102:103], s[46:47], v45, s23, v[46:47]
	global_load_dword v41, v[102:103], off nt
	v_or_b32_e32 v45, s22, v97
	v_mad_i64_i32 v[104:105], s[46:47], v45, s23, v[46:47]
	global_load_dword v43, v[104:105], off nt
	s_mov_b64 exec, s[28:29]
	v_add_u32_e32 v39, v53, v54
	s_waitcnt vmcnt(30)
	ds_write2_b32 v39, v108, v109 offset1:66
	v_add_u32_e32 v39, v53, v57
	s_waitcnt vmcnt(28)
	ds_write2_b32 v39, v110, v111 offset1:66
	v_add_u32_e32 v39, v53, v60
	s_waitcnt vmcnt(26)
	ds_write2_b32 v39, v112, v113 offset1:66
	v_add_u32_e32 v39, v53, v63
	s_waitcnt vmcnt(24)
	ds_write2_b32 v39, v114, v115 offset1:66
	v_add_u32_e32 v39, v53, v66
	s_waitcnt vmcnt(22)
	ds_write2_b32 v39, v116, v117 offset1:66
	v_add_u32_e32 v39, v53, v69
	s_waitcnt vmcnt(20)
	ds_write2_b32 v39, v118, v119 offset1:66
	v_add_u32_e32 v39, v53, v72
	s_waitcnt vmcnt(18)
	ds_write2_b32 v39, v120, v121 offset1:66
	v_add_u32_e32 v39, v53, v75
	s_waitcnt vmcnt(16)
	ds_write2_b32 v39, v122, v123 offset1:66
	v_add_u32_e32 v39, v53, v78
	s_waitcnt vmcnt(14)
	ds_write2_b32 v39, v124, v125 offset1:66
	v_add_u32_e32 v39, v53, v81
	s_waitcnt vmcnt(12)
	ds_write2_b32 v39, v126, v127 offset1:66
	v_add_u32_e32 v39, v53, v84
	s_waitcnt vmcnt(10)
	ds_write2_b32 v39, v128, v129 offset1:66
	v_add_u32_e32 v39, v53, v87
	s_waitcnt vmcnt(8)
	ds_write2_b32 v39, v130, v131 offset1:66
	v_add_u32_e32 v39, v53, v90
	s_waitcnt vmcnt(6)
	ds_write2_b32 v39, v132, v133 offset1:66
	s_waitcnt vmcnt(4)
	ds_write2_b32 v39, v134, v135 offset0:132 offset1:198
	v_add_u32_e32 v39, 0x400, v39
	s_waitcnt vmcnt(2)
	ds_write2_b32 v39, v136, v137 offset0:8 offset1:74
	s_mov_b64 s[28:29], 0
	s_branch .LBB0_212
